# parameter-vector prefetch during the preceding grid barrier extended to P6 (conv taps) and P12, lambda vectors fetched during the pre-attention barrier; wave index parked in a spill lane; on top of v1
# speedup vs baseline: 1.0028x; 1.0021x over previous
; #define LAS __attribute__((address_space(3)))
; __device__ __forceinline__ float fast_sigmoid(float x) { return __builtin_amdgcn_rcpf(1.0f + __builtin_amdgcn_exp2f(-1.4426950408889634f * x)); }
; __global__ void __launch_bounds__(NTHREADS) fwd_megakernel(Args a) {
;     ...
;     const int tid = threadIdx.x, lane = tid & 63, wave = __builtin_amdgcn_readfirstlane(tid >> 6);
;     ...
;         LAS float* sil = (LAS float*)ldsl;
;         LAS float* red = (LAS float*)(ldsl + 12288);
;         for (int idx = tid; idx < 3072; idx += NTHREADS) { const int v = idx >> 10, k = idx & 1023; const float cv = (v < 2) ? a.c[v * DM + k] : a.c_ctx[k]; sil[idx] = cv * fast_sigmoid(cv); }
;         __syncthreads();
;         const bool act = lane < 36; const int j = bx * 36 + (act ? lane : 0), kb = wave * 128;
;         float s0 = 0.f, s1 = 0.f, s2 = 0.f;
;         if (act) {
; #pragma unroll 8
;         for (int kk = 0; kk < 128; ++kk) { const float w = __builtin_nontemporal_load(a.w_mod + (size_t)(kb + kk) * NMOD + j); s0 += sil[kb + kk] * w; s1 += sil[1024 + kb + kk] * w; s2 += sil[2048 + kb + kk] * w; }
;         }
.LBB0_7:
	s_load_dwordx16 s[68:83], s[0:1], 0x40
	s_load_dwordx16 s[52:67], s[0:1], 0x80
	v_mov_b32_e32 v3, 0
	v_lshlrev_b32_e32 v2, 2, v160
	s_waitcnt lgkmcnt(0)
	v_lshl_add_u64 v[4:5], s[38:39], 0, v[2:3]
	v_lshl_add_u64 v[8:9], s[42:43], 0, v[2:3]
	s_mov_b64 s[4:5], 0x1000
	v_lshl_add_u64 v[6:7], v[4:5], 0, s[4:5]
	v_add_u32_e32 v1, 0, v2
	global_load_dword v10, v[4:5], off
	global_load_dword v11, v[4:5], off offset:2048
	global_load_dword v12, v[6:7], off
	global_load_dword v13, v[6:7], off offset:2048
	global_load_dword v14, v[8:9], off
	global_load_dword v15, v[8:9], off offset:2048
	s_waitcnt vmcnt(5)
	v_mul_f32_e32 v16, 0xbfb8aa3b, v10
	v_exp_f32_e32 v16, v16
	s_nop 0
	v_add_f32_e32 v16, 1.0, v16
	v_rcp_f32_e32 v16, v16
	s_nop 0
	v_mul_f32_e32 v10, v10, v16
	ds_write_b32 v1, v10
	s_waitcnt vmcnt(4)
	v_mul_f32_e32 v16, 0xbfb8aa3b, v11
	v_exp_f32_e32 v16, v16
	s_nop 0
	v_add_f32_e32 v16, 1.0, v16
	v_rcp_f32_e32 v16, v16
	s_nop 0
	v_mul_f32_e32 v11, v11, v16
	ds_write_b32 v1, v11 offset:2048
	s_waitcnt vmcnt(3)
	v_mul_f32_e32 v16, 0xbfb8aa3b, v12
	v_exp_f32_e32 v16, v16
	s_nop 0
	v_add_f32_e32 v16, 1.0, v16
	v_rcp_f32_e32 v16, v16
	s_nop 0
	v_mul_f32_e32 v12, v12, v16
	ds_write_b32 v1, v12 offset:4096
	s_waitcnt vmcnt(2)
	v_mul_f32_e32 v16, 0xbfb8aa3b, v13
	v_exp_f32_e32 v16, v16
	s_nop 0
	v_add_f32_e32 v16, 1.0, v16
	v_rcp_f32_e32 v16, v16
	s_nop 0
	v_mul_f32_e32 v13, v13, v16
	ds_write_b32 v1, v13 offset:6144
	s_waitcnt vmcnt(1)
	v_mul_f32_e32 v16, 0xbfb8aa3b, v14
	v_exp_f32_e32 v16, v16
	s_nop 0
	v_add_f32_e32 v16, 1.0, v16
	v_rcp_f32_e32 v16, v16
	s_nop 0
	v_mul_f32_e32 v14, v14, v16
	ds_write_b32 v1, v14 offset:8192
	s_waitcnt vmcnt(0)
	v_mul_f32_e32 v16, 0xbfb8aa3b, v15
	v_exp_f32_e32 v16, v16
	s_nop 0
	v_add_f32_e32 v16, 1.0, v16
	v_rcp_f32_e32 v16, v16
	s_nop 0
	v_mul_f32_e32 v15, v15, v16
	ds_write_b32 v1, v15 offset:10240
	v_and_b32_e32 v161, 63, v160
	v_cmp_gt_u32_e32 vcc, 36, v161
	v_mov_b32_e32 v5, 0
	s_lshr_b32 s21, s16, 6
	v_writelane_b32 v238, s21, 40
	v_cndmask_b32_e32 v2, 0, v161, vcc
	s_and_b32 s98, s20, 7
	s_lshl_b32 s98, s98, 5
	s_lshr_b32 s99, s20, 3
	s_add_i32 s98, s98, s99
	v_mad_u64_u32 v[2:3], s[0:1], s98, 36, v[2:3]
	v_ashrrev_i32_e32 v3, 31, v2
	v_mov_b32_e32 v4, v5
	v_mov_b32_e32 v1, v5
	s_waitcnt lgkmcnt(0)
	s_barrier
	s_and_saveexec_b64 s[4:5], vcc
	s_cbranch_execz .LBB0_12
	s_lshl_b32 s1, s21, 9
	s_lshl_b32 s0, s21, 7
	s_add_i32 s3, s1, 0
	s_mul_i32 s1, s21, 0x480000
	s_mul_hi_u32 s6, s0, 0x9000
	s_add_u32 s0, s44, s1
	s_addc_u32 s1, s45, s6
	v_lshlrev_b32_e32 v6, 2, v2
	v_mov_b32_e32 v1, 0
	v_mov_b32_e32 v4, 0
	v_mov_b32_e32 v5, 0
	global_load_dword v32, v6, s[0:1] nt
	s_add_u32 s0, s0, 0x9000
	s_addc_u32 s1, s1, 0
	global_load_dword v33, v6, s[0:1] nt
	s_add_u32 s0, s0, 0x9000
	s_addc_u32 s1, s1, 0
	global_load_dword v34, v6, s[0:1] nt
	s_add_u32 s0, s0, 0x9000
	s_addc_u32 s1, s1, 0
	global_load_dword v35, v6, s[0:1] nt
	s_add_u32 s0, s0, 0x9000
	s_addc_u32 s1, s1, 0
	global_load_dword v36, v6, s[0:1] nt
	s_add_u32 s0, s0, 0x9000
	s_addc_u32 s1, s1, 0
	global_load_dword v37, v6, s[0:1] nt
	s_add_u32 s0, s0, 0x9000
	s_addc_u32 s1, s1, 0
	global_load_dword v38, v6, s[0:1] nt
	s_add_u32 s0, s0, 0x9000
	s_addc_u32 s1, s1, 0
	global_load_dword v39, v6, s[0:1] nt
	s_add_u32 s0, s0, 0x9000
	s_addc_u32 s1, s1, 0
	global_load_dword v40, v6, s[0:1] nt
	s_add_u32 s0, s0, 0x9000
	s_addc_u32 s1, s1, 0
	global_load_dword v41, v6, s[0:1] nt
	s_add_u32 s0, s0, 0x9000
	s_addc_u32 s1, s1, 0
	global_load_dword v42, v6, s[0:1] nt
	s_add_u32 s0, s0, 0x9000
	s_addc_u32 s1, s1, 0
	global_load_dword v43, v6, s[0:1] nt
	s_add_u32 s0, s0, 0x9000
	s_addc_u32 s1, s1, 0
	global_load_dword v44, v6, s[0:1] nt
	s_add_u32 s0, s0, 0x9000
	s_addc_u32 s1, s1, 0
	global_load_dword v45, v6, s[0:1] nt
	s_add_u32 s0, s0, 0x9000
	s_addc_u32 s1, s1, 0
	global_load_dword v46, v6, s[0:1] nt
	s_add_u32 s0, s0, 0x9000
	s_addc_u32 s1, s1, 0
	global_load_dword v47, v6, s[0:1] nt
	s_add_u32 s0, s0, 0x9000
	s_addc_u32 s1, s1, 0
	global_load_dword v48, v6, s[0:1] nt
	s_add_u32 s0, s0, 0x9000
	s_addc_u32 s1, s1, 0
	global_load_dword v49, v6, s[0:1] nt
	s_add_u32 s0, s0, 0x9000
	s_addc_u32 s1, s1, 0
	global_load_dword v50, v6, s[0:1] nt
	s_add_u32 s0, s0, 0x9000
	s_addc_u32 s1, s1, 0
	global_load_dword v51, v6, s[0:1] nt
	s_add_u32 s0, s0, 0x9000
	s_addc_u32 s1, s1, 0
	global_load_dword v52, v6, s[0:1] nt
	s_add_u32 s0, s0, 0x9000
	s_addc_u32 s1, s1, 0
	global_load_dword v53, v6, s[0:1] nt
	s_add_u32 s0, s0, 0x9000
	s_addc_u32 s1, s1, 0
	global_load_dword v54, v6, s[0:1] nt
	s_add_u32 s0, s0, 0x9000
	s_addc_u32 s1, s1, 0
	global_load_dword v55, v6, s[0:1] nt
	s_add_u32 s0, s0, 0x9000
	s_addc_u32 s1, s1, 0
	global_load_dword v56, v6, s[0:1] nt
	s_add_u32 s0, s0, 0x9000
	s_addc_u32 s1, s1, 0
	global_load_dword v57, v6, s[0:1] nt
	s_add_u32 s0, s0, 0x9000
	s_addc_u32 s1, s1, 0
	global_load_dword v58, v6, s[0:1] nt
	s_add_u32 s0, s0, 0x9000
	s_addc_u32 s1, s1, 0
	global_load_dword v59, v6, s[0:1] nt
	s_add_u32 s0, s0, 0x9000
	s_addc_u32 s1, s1, 0
	global_load_dword v60, v6, s[0:1] nt
	s_add_u32 s0, s0, 0x9000
	s_addc_u32 s1, s1, 0
	global_load_dword v61, v6, s[0:1] nt
	s_add_u32 s0, s0, 0x9000
	s_addc_u32 s1, s1, 0
	global_load_dword v62, v6, s[0:1] nt
	s_add_u32 s0, s0, 0x9000
	s_addc_u32 s1, s1, 0
	global_load_dword v63, v6, s[0:1] nt
	s_add_u32 s0, s0, 0x9000
	s_addc_u32 s1, s1, 0
	global_load_dword v64, v6, s[0:1] nt
	s_add_u32 s0, s0, 0x9000
	s_addc_u32 s1, s1, 0
	global_load_dword v65, v6, s[0:1] nt
	s_add_u32 s0, s0, 0x9000
	s_addc_u32 s1, s1, 0
	global_load_dword v66, v6, s[0:1] nt
	s_add_u32 s0, s0, 0x9000
	s_addc_u32 s1, s1, 0
; __global__ void __launch_bounds__(NTHREADS) fwd_megakernel(Args a) {
;     ...
;         if (act) {
; #pragma unroll 8
;         for (int kk = 0; kk < 128; ++kk) { const float w = __builtin_nontemporal_load(a.w_mod + (size_t)(kb + kk) * NMOD + j); s0 += sil[kb + kk] * w; s1 += sil[1024 + kb + kk] * w; s2 += sil[2048 + kb + kk] * w; }
;         }
	global_load_dword v67, v6, s[0:1] nt
	s_add_u32 s0, s0, 0x9000
	s_addc_u32 s1, s1, 0
	global_load_dword v68, v6, s[0:1] nt
	s_add_u32 s0, s0, 0x9000
	s_addc_u32 s1, s1, 0
	global_load_dword v69, v6, s[0:1] nt
	s_add_u32 s0, s0, 0x9000
	s_addc_u32 s1, s1, 0
	global_load_dword v70, v6, s[0:1] nt
	s_add_u32 s0, s0, 0x9000
	s_addc_u32 s1, s1, 0
	global_load_dword v71, v6, s[0:1] nt
	s_add_u32 s0, s0, 0x9000
	s_addc_u32 s1, s1, 0
	global_load_dword v72, v6, s[0:1] nt
	s_add_u32 s0, s0, 0x9000
	s_addc_u32 s1, s1, 0
	global_load_dword v73, v6, s[0:1] nt
	s_add_u32 s0, s0, 0x9000
	s_addc_u32 s1, s1, 0
	global_load_dword v74, v6, s[0:1] nt
	s_add_u32 s0, s0, 0x9000
	s_addc_u32 s1, s1, 0
	global_load_dword v75, v6, s[0:1] nt
	s_add_u32 s0, s0, 0x9000
	s_addc_u32 s1, s1, 0
	global_load_dword v76, v6, s[0:1] nt
	s_add_u32 s0, s0, 0x9000
	s_addc_u32 s1, s1, 0
	global_load_dword v77, v6, s[0:1] nt
	s_add_u32 s0, s0, 0x9000
	s_addc_u32 s1, s1, 0
	global_load_dword v78, v6, s[0:1] nt
	s_add_u32 s0, s0, 0x9000
	s_addc_u32 s1, s1, 0
	global_load_dword v79, v6, s[0:1] nt
	s_add_u32 s0, s0, 0x9000
	s_addc_u32 s1, s1, 0
	global_load_dword v80, v6, s[0:1] nt
	s_add_u32 s0, s0, 0x9000
	s_addc_u32 s1, s1, 0
	global_load_dword v81, v6, s[0:1] nt
	s_add_u32 s0, s0, 0x9000
	s_addc_u32 s1, s1, 0
	global_load_dword v82, v6, s[0:1] nt
	s_add_u32 s0, s0, 0x9000
	s_addc_u32 s1, s1, 0
	global_load_dword v83, v6, s[0:1] nt
	s_add_u32 s0, s0, 0x9000
	s_addc_u32 s1, s1, 0
	global_load_dword v84, v6, s[0:1] nt
	s_add_u32 s0, s0, 0x9000
	s_addc_u32 s1, s1, 0
	global_load_dword v85, v6, s[0:1] nt
	s_add_u32 s0, s0, 0x9000
	s_addc_u32 s1, s1, 0
	global_load_dword v86, v6, s[0:1] nt
	s_add_u32 s0, s0, 0x9000
	s_addc_u32 s1, s1, 0
	global_load_dword v87, v6, s[0:1] nt
	s_add_u32 s0, s0, 0x9000
	s_addc_u32 s1, s1, 0
	v_mov_b32_e32 v28, s3
	ds_read_b128 v[8:11], v28
	ds_read_b128 v[12:15], v28 offset:16
	ds_read_b128 v[16:19], v28 offset:4096
	ds_read_b128 v[20:23], v28 offset:4112
	ds_read_b128 v[24:27], v28 offset:8192
	ds_read_b128 v[28:31], v28 offset:8208
	s_add_i32 s3, s3, 32
	s_waitcnt lgkmcnt(0)
	s_waitcnt vmcnt(55)
	v_fmac_f32_e32 v1, v32, v8
	v_fmac_f32_e32 v5, v32, v16
	v_fmac_f32_e32 v4, v32, v24
	global_load_dword v88, v6, s[0:1] nt
	s_add_u32 s0, s0, 0x9000
	s_addc_u32 s1, s1, 0
	s_waitcnt vmcnt(55)
	v_fmac_f32_e32 v1, v33, v9
	v_fmac_f32_e32 v5, v33, v17
	v_fmac_f32_e32 v4, v33, v25
	global_load_dword v89, v6, s[0:1] nt
	s_add_u32 s0, s0, 0x9000
	s_addc_u32 s1, s1, 0
	s_waitcnt vmcnt(55)
	v_fmac_f32_e32 v1, v34, v10
	v_fmac_f32_e32 v5, v34, v18
	v_fmac_f32_e32 v4, v34, v26
	global_load_dword v90, v6, s[0:1] nt
	s_add_u32 s0, s0, 0x9000
	s_addc_u32 s1, s1, 0
	s_waitcnt vmcnt(55)
	v_fmac_f32_e32 v1, v35, v11
	v_fmac_f32_e32 v5, v35, v19
	v_fmac_f32_e32 v4, v35, v27
	global_load_dword v91, v6, s[0:1] nt
	s_add_u32 s0, s0, 0x9000
	s_addc_u32 s1, s1, 0
	s_waitcnt vmcnt(55)
	v_fmac_f32_e32 v1, v36, v12
	v_fmac_f32_e32 v5, v36, v20
	v_fmac_f32_e32 v4, v36, v28
	global_load_dword v92, v6, s[0:1] nt
	s_add_u32 s0, s0, 0x9000
	s_addc_u32 s1, s1, 0
	s_waitcnt vmcnt(55)
	v_fmac_f32_e32 v1, v37, v13
	v_fmac_f32_e32 v5, v37, v21
	v_fmac_f32_e32 v4, v37, v29
	global_load_dword v93, v6, s[0:1] nt
	s_add_u32 s0, s0, 0x9000
	s_addc_u32 s1, s1, 0
	s_waitcnt vmcnt(55)
	v_fmac_f32_e32 v1, v38, v14
	v_fmac_f32_e32 v5, v38, v22
	v_fmac_f32_e32 v4, v38, v30
	global_load_dword v94, v6, s[0:1] nt
	s_add_u32 s0, s0, 0x9000
	s_addc_u32 s1, s1, 0
	s_waitcnt vmcnt(55)
	v_fmac_f32_e32 v1, v39, v15
	v_fmac_f32_e32 v5, v39, v23
	v_fmac_f32_e32 v4, v39, v31
	global_load_dword v95, v6, s[0:1] nt
	s_add_u32 s0, s0, 0x9000
	s_addc_u32 s1, s1, 0
	v_mov_b32_e32 v28, s3
	ds_read_b128 v[8:11], v28
	ds_read_b128 v[12:15], v28 offset:16
	ds_read_b128 v[16:19], v28 offset:4096
	ds_read_b128 v[20:23], v28 offset:4112
	ds_read_b128 v[24:27], v28 offset:8192
	ds_read_b128 v[28:31], v28 offset:8208
	s_add_i32 s3, s3, 32
	s_waitcnt lgkmcnt(0)
	s_waitcnt vmcnt(55)
	v_fmac_f32_e32 v1, v40, v8
	v_fmac_f32_e32 v5, v40, v16
	v_fmac_f32_e32 v4, v40, v24
	global_load_dword v96, v6, s[0:1] nt
	s_add_u32 s0, s0, 0x9000
	s_addc_u32 s1, s1, 0
	s_waitcnt vmcnt(55)
	v_fmac_f32_e32 v1, v41, v9
	v_fmac_f32_e32 v5, v41, v17
	v_fmac_f32_e32 v4, v41, v25
	global_load_dword v97, v6, s[0:1] nt
	s_add_u32 s0, s0, 0x9000
	s_addc_u32 s1, s1, 0
	s_waitcnt vmcnt(55)
	v_fmac_f32_e32 v1, v42, v10
	v_fmac_f32_e32 v5, v42, v18
	v_fmac_f32_e32 v4, v42, v26
	global_load_dword v98, v6, s[0:1] nt
	s_add_u32 s0, s0, 0x9000
	s_addc_u32 s1, s1, 0
	s_waitcnt vmcnt(55)
	v_fmac_f32_e32 v1, v43, v11
	v_fmac_f32_e32 v5, v43, v19
	v_fmac_f32_e32 v4, v43, v27
	global_load_dword v99, v6, s[0:1] nt
	s_add_u32 s0, s0, 0x9000
	s_addc_u32 s1, s1, 0
	s_waitcnt vmcnt(55)
	v_fmac_f32_e32 v1, v44, v12
	v_fmac_f32_e32 v5, v44, v20
	v_fmac_f32_e32 v4, v44, v28
	global_load_dword v100, v6, s[0:1] nt
	s_add_u32 s0, s0, 0x9000
	s_addc_u32 s1, s1, 0
	s_waitcnt vmcnt(55)
	v_fmac_f32_e32 v1, v45, v13
	v_fmac_f32_e32 v5, v45, v21
	v_fmac_f32_e32 v4, v45, v29
	global_load_dword v101, v6, s[0:1] nt
	s_add_u32 s0, s0, 0x9000
	s_addc_u32 s1, s1, 0
	s_waitcnt vmcnt(55)
	v_fmac_f32_e32 v1, v46, v14
	v_fmac_f32_e32 v5, v46, v22
	v_fmac_f32_e32 v4, v46, v30
	global_load_dword v102, v6, s[0:1] nt
	s_add_u32 s0, s0, 0x9000
	s_addc_u32 s1, s1, 0
	s_waitcnt vmcnt(55)
	v_fmac_f32_e32 v1, v47, v15
	v_fmac_f32_e32 v5, v47, v23
	v_fmac_f32_e32 v4, v47, v31
	global_load_dword v103, v6, s[0:1] nt
	s_add_u32 s0, s0, 0x9000
	s_addc_u32 s1, s1, 0
	v_mov_b32_e32 v28, s3
	ds_read_b128 v[8:11], v28
	ds_read_b128 v[12:15], v28 offset:16
	ds_read_b128 v[16:19], v28 offset:4096
	ds_read_b128 v[20:23], v28 offset:4112
	ds_read_b128 v[24:27], v28 offset:8192
	ds_read_b128 v[28:31], v28 offset:8208
	s_add_i32 s3, s3, 32
	s_waitcnt lgkmcnt(0)
; __global__ void __launch_bounds__(NTHREADS) fwd_megakernel(Args a) {
;     ...
;         const bool act = lane < 36; const int j = bx * 36 + (act ? lane : 0), kb = wave * 128;
;         float s0 = 0.f, s1 = 0.f, s2 = 0.f;
;         if (act) {
; #pragma unroll 8
;         for (int kk = 0; kk < 128; ++kk) { const float w = __builtin_nontemporal_load(a.w_mod + (size_t)(kb + kk) * NMOD + j); s0 += sil[kb + kk] * w; s1 += sil[1024 + kb + kk] * w; s2 += sil[2048 + kb + kk] * w; }
;         }
	s_waitcnt vmcnt(55)
	v_fmac_f32_e32 v1, v48, v8
	v_fmac_f32_e32 v5, v48, v16
	v_fmac_f32_e32 v4, v48, v24
	global_load_dword v104, v6, s[0:1] nt
	s_add_u32 s0, s0, 0x9000
	s_addc_u32 s1, s1, 0
	s_waitcnt vmcnt(55)
	v_fmac_f32_e32 v1, v49, v9
	v_fmac_f32_e32 v5, v49, v17
	v_fmac_f32_e32 v4, v49, v25
	global_load_dword v105, v6, s[0:1] nt
	s_add_u32 s0, s0, 0x9000
	s_addc_u32 s1, s1, 0
	s_waitcnt vmcnt(55)
	v_fmac_f32_e32 v1, v50, v10
	v_fmac_f32_e32 v5, v50, v18
	v_fmac_f32_e32 v4, v50, v26
	global_load_dword v106, v6, s[0:1] nt
	s_add_u32 s0, s0, 0x9000
	s_addc_u32 s1, s1, 0
	s_waitcnt vmcnt(55)
	v_fmac_f32_e32 v1, v51, v11
	v_fmac_f32_e32 v5, v51, v19
	v_fmac_f32_e32 v4, v51, v27
	global_load_dword v107, v6, s[0:1] nt
	s_add_u32 s0, s0, 0x9000
	s_addc_u32 s1, s1, 0
	s_waitcnt vmcnt(55)
	v_fmac_f32_e32 v1, v52, v12
	v_fmac_f32_e32 v5, v52, v20
	v_fmac_f32_e32 v4, v52, v28
	global_load_dword v108, v6, s[0:1] nt
	s_add_u32 s0, s0, 0x9000
	s_addc_u32 s1, s1, 0
	s_waitcnt vmcnt(55)
	v_fmac_f32_e32 v1, v53, v13
	v_fmac_f32_e32 v5, v53, v21
	v_fmac_f32_e32 v4, v53, v29
	global_load_dword v109, v6, s[0:1] nt
	s_add_u32 s0, s0, 0x9000
	s_addc_u32 s1, s1, 0
	s_waitcnt vmcnt(55)
	v_fmac_f32_e32 v1, v54, v14
	v_fmac_f32_e32 v5, v54, v22
	v_fmac_f32_e32 v4, v54, v30
	global_load_dword v110, v6, s[0:1] nt
	s_add_u32 s0, s0, 0x9000
	s_addc_u32 s1, s1, 0
	s_waitcnt vmcnt(55)
	v_fmac_f32_e32 v1, v55, v15
	v_fmac_f32_e32 v5, v55, v23
	v_fmac_f32_e32 v4, v55, v31
	global_load_dword v111, v6, s[0:1] nt
	s_add_u32 s0, s0, 0x9000
	s_addc_u32 s1, s1, 0
	v_mov_b32_e32 v28, s3
	ds_read_b128 v[8:11], v28
	ds_read_b128 v[12:15], v28 offset:16
	ds_read_b128 v[16:19], v28 offset:4096
	ds_read_b128 v[20:23], v28 offset:4112
	ds_read_b128 v[24:27], v28 offset:8192
	ds_read_b128 v[28:31], v28 offset:8208
	s_add_i32 s3, s3, 32
	s_waitcnt lgkmcnt(0)
	s_waitcnt vmcnt(55)
	v_fmac_f32_e32 v1, v56, v8
	v_fmac_f32_e32 v5, v56, v16
	v_fmac_f32_e32 v4, v56, v24
	global_load_dword v112, v6, s[0:1] nt
	s_add_u32 s0, s0, 0x9000
	s_addc_u32 s1, s1, 0
	s_waitcnt vmcnt(55)
	v_fmac_f32_e32 v1, v57, v9
	v_fmac_f32_e32 v5, v57, v17
	v_fmac_f32_e32 v4, v57, v25
	global_load_dword v113, v6, s[0:1] nt
	s_add_u32 s0, s0, 0x9000
	s_addc_u32 s1, s1, 0
	s_waitcnt vmcnt(55)
	v_fmac_f32_e32 v1, v58, v10
	v_fmac_f32_e32 v5, v58, v18
	v_fmac_f32_e32 v4, v58, v26
	global_load_dword v114, v6, s[0:1] nt
	s_add_u32 s0, s0, 0x9000
	s_addc_u32 s1, s1, 0
	s_waitcnt vmcnt(55)
	v_fmac_f32_e32 v1, v59, v11
	v_fmac_f32_e32 v5, v59, v19
	v_fmac_f32_e32 v4, v59, v27
	global_load_dword v115, v6, s[0:1] nt
	s_add_u32 s0, s0, 0x9000
	s_addc_u32 s1, s1, 0
	s_waitcnt vmcnt(55)
	v_fmac_f32_e32 v1, v60, v12
	v_fmac_f32_e32 v5, v60, v20
	v_fmac_f32_e32 v4, v60, v28
	global_load_dword v116, v6, s[0:1] nt
	s_add_u32 s0, s0, 0x9000
	s_addc_u32 s1, s1, 0
	s_waitcnt vmcnt(55)
	v_fmac_f32_e32 v1, v61, v13
	v_fmac_f32_e32 v5, v61, v21
	v_fmac_f32_e32 v4, v61, v29
	global_load_dword v117, v6, s[0:1] nt
	s_add_u32 s0, s0, 0x9000
	s_addc_u32 s1, s1, 0
	s_waitcnt vmcnt(55)
	v_fmac_f32_e32 v1, v62, v14
	v_fmac_f32_e32 v5, v62, v22
	v_fmac_f32_e32 v4, v62, v30
	global_load_dword v118, v6, s[0:1] nt
	s_add_u32 s0, s0, 0x9000
	s_addc_u32 s1, s1, 0
	s_waitcnt vmcnt(55)
	v_fmac_f32_e32 v1, v63, v15
	v_fmac_f32_e32 v5, v63, v23
	v_fmac_f32_e32 v4, v63, v31
	global_load_dword v119, v6, s[0:1] nt
	s_add_u32 s0, s0, 0x9000
	s_addc_u32 s1, s1, 0
	v_mov_b32_e32 v28, s3
	ds_read_b128 v[8:11], v28
	ds_read_b128 v[12:15], v28 offset:16
	ds_read_b128 v[16:19], v28 offset:4096
	ds_read_b128 v[20:23], v28 offset:4112
	ds_read_b128 v[24:27], v28 offset:8192
	ds_read_b128 v[28:31], v28 offset:8208
	s_add_i32 s3, s3, 32
	s_waitcnt lgkmcnt(0)
	s_waitcnt vmcnt(55)
	v_fmac_f32_e32 v1, v64, v8
	v_fmac_f32_e32 v5, v64, v16
	v_fmac_f32_e32 v4, v64, v24
	global_load_dword v120, v6, s[0:1] nt
	s_add_u32 s0, s0, 0x9000
	s_addc_u32 s1, s1, 0
	s_waitcnt vmcnt(55)
	v_fmac_f32_e32 v1, v65, v9
	v_fmac_f32_e32 v5, v65, v17
	v_fmac_f32_e32 v4, v65, v25
	global_load_dword v121, v6, s[0:1] nt
	s_add_u32 s0, s0, 0x9000
	s_addc_u32 s1, s1, 0
	s_waitcnt vmcnt(55)
	v_fmac_f32_e32 v1, v66, v10
	v_fmac_f32_e32 v5, v66, v18
	v_fmac_f32_e32 v4, v66, v26
	global_load_dword v122, v6, s[0:1] nt
	s_add_u32 s0, s0, 0x9000
	s_addc_u32 s1, s1, 0
	s_waitcnt vmcnt(55)
	v_fmac_f32_e32 v1, v67, v11
	v_fmac_f32_e32 v5, v67, v19
	v_fmac_f32_e32 v4, v67, v27
	global_load_dword v123, v6, s[0:1] nt
	s_add_u32 s0, s0, 0x9000
	s_addc_u32 s1, s1, 0
	s_waitcnt vmcnt(55)
	v_fmac_f32_e32 v1, v68, v12
	v_fmac_f32_e32 v5, v68, v20
	v_fmac_f32_e32 v4, v68, v28
	global_load_dword v124, v6, s[0:1] nt
	s_add_u32 s0, s0, 0x9000
	s_addc_u32 s1, s1, 0
	s_waitcnt vmcnt(55)
	v_fmac_f32_e32 v1, v69, v13
	v_fmac_f32_e32 v5, v69, v21
	v_fmac_f32_e32 v4, v69, v29
	global_load_dword v125, v6, s[0:1] nt
	s_add_u32 s0, s0, 0x9000
	s_addc_u32 s1, s1, 0
	s_waitcnt vmcnt(55)
	v_fmac_f32_e32 v1, v70, v14
	v_fmac_f32_e32 v5, v70, v22
	v_fmac_f32_e32 v4, v70, v30
	global_load_dword v126, v6, s[0:1] nt
	s_add_u32 s0, s0, 0x9000
	s_addc_u32 s1, s1, 0
	s_waitcnt vmcnt(55)
	v_fmac_f32_e32 v1, v71, v15
	v_fmac_f32_e32 v5, v71, v23
	v_fmac_f32_e32 v4, v71, v31
	global_load_dword v127, v6, s[0:1] nt
	s_add_u32 s0, s0, 0x9000
	s_addc_u32 s1, s1, 0
	v_mov_b32_e32 v28, s3
	ds_read_b128 v[8:11], v28
	ds_read_b128 v[12:15], v28 offset:16
	ds_read_b128 v[16:19], v28 offset:4096
	ds_read_b128 v[20:23], v28 offset:4112
	ds_read_b128 v[24:27], v28 offset:8192
	ds_read_b128 v[28:31], v28 offset:8208
	s_add_i32 s3, s3, 32
	s_waitcnt lgkmcnt(0)
	s_waitcnt vmcnt(55)
; __global__ void __launch_bounds__(NTHREADS) fwd_megakernel(Args a) {
;     ...
;         const bool act = lane < 36; const int j = bx * 36 + (act ? lane : 0), kb = wave * 128;
;         float s0 = 0.f, s1 = 0.f, s2 = 0.f;
;         if (act) {
; #pragma unroll 8
;         for (int kk = 0; kk < 128; ++kk) { const float w = __builtin_nontemporal_load(a.w_mod + (size_t)(kb + kk) * NMOD + j); s0 += sil[kb + kk] * w; s1 += sil[1024 + kb + kk] * w; s2 += sil[2048 + kb + kk] * w; }
;         }
	v_fmac_f32_e32 v1, v72, v8
	v_fmac_f32_e32 v5, v72, v16
	v_fmac_f32_e32 v4, v72, v24
	global_load_dword v128, v6, s[0:1] nt
	s_add_u32 s0, s0, 0x9000
	s_addc_u32 s1, s1, 0
	s_waitcnt vmcnt(55)
	v_fmac_f32_e32 v1, v73, v9
	v_fmac_f32_e32 v5, v73, v17
	v_fmac_f32_e32 v4, v73, v25
	global_load_dword v129, v6, s[0:1] nt
	s_add_u32 s0, s0, 0x9000
	s_addc_u32 s1, s1, 0
	s_waitcnt vmcnt(55)
	v_fmac_f32_e32 v1, v74, v10
	v_fmac_f32_e32 v5, v74, v18
	v_fmac_f32_e32 v4, v74, v26
	global_load_dword v130, v6, s[0:1] nt
	s_add_u32 s0, s0, 0x9000
	s_addc_u32 s1, s1, 0
	s_waitcnt vmcnt(55)
	v_fmac_f32_e32 v1, v75, v11
	v_fmac_f32_e32 v5, v75, v19
	v_fmac_f32_e32 v4, v75, v27
	global_load_dword v131, v6, s[0:1] nt
	s_add_u32 s0, s0, 0x9000
	s_addc_u32 s1, s1, 0
	s_waitcnt vmcnt(55)
	v_fmac_f32_e32 v1, v76, v12
	v_fmac_f32_e32 v5, v76, v20
	v_fmac_f32_e32 v4, v76, v28
	global_load_dword v132, v6, s[0:1] nt
	s_add_u32 s0, s0, 0x9000
	s_addc_u32 s1, s1, 0
	s_waitcnt vmcnt(55)
	v_fmac_f32_e32 v1, v77, v13
	v_fmac_f32_e32 v5, v77, v21
	v_fmac_f32_e32 v4, v77, v29
	global_load_dword v133, v6, s[0:1] nt
	s_add_u32 s0, s0, 0x9000
	s_addc_u32 s1, s1, 0
	s_waitcnt vmcnt(55)
	v_fmac_f32_e32 v1, v78, v14
	v_fmac_f32_e32 v5, v78, v22
	v_fmac_f32_e32 v4, v78, v30
	global_load_dword v134, v6, s[0:1] nt
	s_add_u32 s0, s0, 0x9000
	s_addc_u32 s1, s1, 0
	s_waitcnt vmcnt(55)
	v_fmac_f32_e32 v1, v79, v15
	v_fmac_f32_e32 v5, v79, v23
	v_fmac_f32_e32 v4, v79, v31
	global_load_dword v135, v6, s[0:1] nt
	s_add_u32 s0, s0, 0x9000
	s_addc_u32 s1, s1, 0
	v_mov_b32_e32 v28, s3
	ds_read_b128 v[8:11], v28
	ds_read_b128 v[12:15], v28 offset:16
	ds_read_b128 v[16:19], v28 offset:4096
	ds_read_b128 v[20:23], v28 offset:4112
	ds_read_b128 v[24:27], v28 offset:8192
	ds_read_b128 v[28:31], v28 offset:8208
	s_add_i32 s3, s3, 32
	s_waitcnt lgkmcnt(0)
	s_waitcnt vmcnt(55)
	v_fmac_f32_e32 v1, v80, v8
	v_fmac_f32_e32 v5, v80, v16
	v_fmac_f32_e32 v4, v80, v24
	global_load_dword v136, v6, s[0:1] nt
	s_add_u32 s0, s0, 0x9000
	s_addc_u32 s1, s1, 0
	s_waitcnt vmcnt(55)
	v_fmac_f32_e32 v1, v81, v9
	v_fmac_f32_e32 v5, v81, v17
	v_fmac_f32_e32 v4, v81, v25
	global_load_dword v137, v6, s[0:1] nt
	s_add_u32 s0, s0, 0x9000
	s_addc_u32 s1, s1, 0
	s_waitcnt vmcnt(55)
	v_fmac_f32_e32 v1, v82, v10
	v_fmac_f32_e32 v5, v82, v18
	v_fmac_f32_e32 v4, v82, v26
	global_load_dword v138, v6, s[0:1] nt
	s_add_u32 s0, s0, 0x9000
	s_addc_u32 s1, s1, 0
	s_waitcnt vmcnt(55)
	v_fmac_f32_e32 v1, v83, v11
	v_fmac_f32_e32 v5, v83, v19
	v_fmac_f32_e32 v4, v83, v27
	global_load_dword v139, v6, s[0:1] nt
	s_add_u32 s0, s0, 0x9000
	s_addc_u32 s1, s1, 0
	s_waitcnt vmcnt(55)
	v_fmac_f32_e32 v1, v84, v12
	v_fmac_f32_e32 v5, v84, v20
	v_fmac_f32_e32 v4, v84, v28
	global_load_dword v140, v6, s[0:1] nt
	s_add_u32 s0, s0, 0x9000
	s_addc_u32 s1, s1, 0
	s_waitcnt vmcnt(55)
	v_fmac_f32_e32 v1, v85, v13
	v_fmac_f32_e32 v5, v85, v21
	v_fmac_f32_e32 v4, v85, v29
	global_load_dword v141, v6, s[0:1] nt
	s_add_u32 s0, s0, 0x9000
	s_addc_u32 s1, s1, 0
	s_waitcnt vmcnt(55)
	v_fmac_f32_e32 v1, v86, v14
	v_fmac_f32_e32 v5, v86, v22
	v_fmac_f32_e32 v4, v86, v30
	global_load_dword v142, v6, s[0:1] nt
	s_add_u32 s0, s0, 0x9000
	s_addc_u32 s1, s1, 0
	s_waitcnt vmcnt(55)
	v_fmac_f32_e32 v1, v87, v15
	v_fmac_f32_e32 v5, v87, v23
	v_fmac_f32_e32 v4, v87, v31
	global_load_dword v143, v6, s[0:1] nt
	s_add_u32 s0, s0, 0x9000
	s_addc_u32 s1, s1, 0
	v_mov_b32_e32 v28, s3
	ds_read_b128 v[8:11], v28
	ds_read_b128 v[12:15], v28 offset:16
	ds_read_b128 v[16:19], v28 offset:4096
	ds_read_b128 v[20:23], v28 offset:4112
	ds_read_b128 v[24:27], v28 offset:8192
	ds_read_b128 v[28:31], v28 offset:8208
	s_add_i32 s3, s3, 32
	s_waitcnt lgkmcnt(0)
	s_waitcnt vmcnt(55)
	v_fmac_f32_e32 v1, v88, v8
	v_fmac_f32_e32 v5, v88, v16
	v_fmac_f32_e32 v4, v88, v24
	global_load_dword v144, v6, s[0:1] nt
	s_add_u32 s0, s0, 0x9000
	s_addc_u32 s1, s1, 0
	s_waitcnt vmcnt(55)
	v_fmac_f32_e32 v1, v89, v9
	v_fmac_f32_e32 v5, v89, v17
	v_fmac_f32_e32 v4, v89, v25
	global_load_dword v145, v6, s[0:1] nt
	s_add_u32 s0, s0, 0x9000
	s_addc_u32 s1, s1, 0
	s_waitcnt vmcnt(55)
	v_fmac_f32_e32 v1, v90, v10
	v_fmac_f32_e32 v5, v90, v18
	v_fmac_f32_e32 v4, v90, v26
	global_load_dword v146, v6, s[0:1] nt
	s_add_u32 s0, s0, 0x9000
	s_addc_u32 s1, s1, 0
	s_waitcnt vmcnt(55)
	v_fmac_f32_e32 v1, v91, v11
	v_fmac_f32_e32 v5, v91, v19
	v_fmac_f32_e32 v4, v91, v27
	global_load_dword v147, v6, s[0:1] nt
	s_add_u32 s0, s0, 0x9000
	s_addc_u32 s1, s1, 0
	s_waitcnt vmcnt(55)
	v_fmac_f32_e32 v1, v92, v12
	v_fmac_f32_e32 v5, v92, v20
	v_fmac_f32_e32 v4, v92, v28
	global_load_dword v148, v6, s[0:1] nt
	s_add_u32 s0, s0, 0x9000
	s_addc_u32 s1, s1, 0
	s_waitcnt vmcnt(55)
	v_fmac_f32_e32 v1, v93, v13
	v_fmac_f32_e32 v5, v93, v21
	v_fmac_f32_e32 v4, v93, v29
	global_load_dword v149, v6, s[0:1] nt
	s_add_u32 s0, s0, 0x9000
	s_addc_u32 s1, s1, 0
	s_waitcnt vmcnt(55)
	v_fmac_f32_e32 v1, v94, v14
	v_fmac_f32_e32 v5, v94, v22
	v_fmac_f32_e32 v4, v94, v30
	global_load_dword v150, v6, s[0:1] nt
	s_add_u32 s0, s0, 0x9000
	s_addc_u32 s1, s1, 0
	s_waitcnt vmcnt(55)
	v_fmac_f32_e32 v1, v95, v15
	v_fmac_f32_e32 v5, v95, v23
	v_fmac_f32_e32 v4, v95, v31
	global_load_dword v151, v6, s[0:1] nt
	s_add_u32 s0, s0, 0x9000
	s_addc_u32 s1, s1, 0
	v_mov_b32_e32 v28, s3
	ds_read_b128 v[8:11], v28
	ds_read_b128 v[12:15], v28 offset:16
	ds_read_b128 v[16:19], v28 offset:4096
	ds_read_b128 v[20:23], v28 offset:4112
	ds_read_b128 v[24:27], v28 offset:8192
	ds_read_b128 v[28:31], v28 offset:8208
	s_add_i32 s3, s3, 32
	s_waitcnt lgkmcnt(0)
	s_waitcnt vmcnt(55)
; __global__ void __launch_bounds__(NTHREADS) fwd_megakernel(Args a) {
;     ...
;         const bool act = lane < 36; const int j = bx * 36 + (act ? lane : 0), kb = wave * 128;
;         float s0 = 0.f, s1 = 0.f, s2 = 0.f;
;         if (act) {
; #pragma unroll 8
;         for (int kk = 0; kk < 128; ++kk) { const float w = __builtin_nontemporal_load(a.w_mod + (size_t)(kb + kk) * NMOD + j); s0 += sil[kb + kk] * w; s1 += sil[1024 + kb + kk] * w; s2 += sil[2048 + kb + kk] * w; }
;         }
	v_fmac_f32_e32 v1, v96, v8
	v_fmac_f32_e32 v5, v96, v16
	v_fmac_f32_e32 v4, v96, v24
	global_load_dword v152, v6, s[0:1] nt
	s_add_u32 s0, s0, 0x9000
	s_addc_u32 s1, s1, 0
	s_waitcnt vmcnt(55)
	v_fmac_f32_e32 v1, v97, v9
	v_fmac_f32_e32 v5, v97, v17
	v_fmac_f32_e32 v4, v97, v25
	global_load_dword v153, v6, s[0:1] nt
	s_add_u32 s0, s0, 0x9000
	s_addc_u32 s1, s1, 0
	s_waitcnt vmcnt(55)
	v_fmac_f32_e32 v1, v98, v10
	v_fmac_f32_e32 v5, v98, v18
	v_fmac_f32_e32 v4, v98, v26
	global_load_dword v154, v6, s[0:1] nt
	s_add_u32 s0, s0, 0x9000
	s_addc_u32 s1, s1, 0
	s_waitcnt vmcnt(55)
	v_fmac_f32_e32 v1, v99, v11
	v_fmac_f32_e32 v5, v99, v19
	v_fmac_f32_e32 v4, v99, v27
	global_load_dword v155, v6, s[0:1] nt
	s_add_u32 s0, s0, 0x9000
	s_addc_u32 s1, s1, 0
	s_waitcnt vmcnt(55)
	v_fmac_f32_e32 v1, v100, v12
	v_fmac_f32_e32 v5, v100, v20
	v_fmac_f32_e32 v4, v100, v28
	global_load_dword v156, v6, s[0:1] nt
	s_add_u32 s0, s0, 0x9000
	s_addc_u32 s1, s1, 0
	s_waitcnt vmcnt(55)
	v_fmac_f32_e32 v1, v101, v13
	v_fmac_f32_e32 v5, v101, v21
	v_fmac_f32_e32 v4, v101, v29
	global_load_dword v157, v6, s[0:1] nt
	s_add_u32 s0, s0, 0x9000
	s_addc_u32 s1, s1, 0
	s_waitcnt vmcnt(55)
	v_fmac_f32_e32 v1, v102, v14
	v_fmac_f32_e32 v5, v102, v22
	v_fmac_f32_e32 v4, v102, v30
	global_load_dword v158, v6, s[0:1] nt
	s_add_u32 s0, s0, 0x9000
	s_addc_u32 s1, s1, 0
	s_waitcnt vmcnt(55)
	v_fmac_f32_e32 v1, v103, v15
	v_fmac_f32_e32 v5, v103, v23
	v_fmac_f32_e32 v4, v103, v31
	global_load_dword v159, v6, s[0:1] nt
	v_mov_b32_e32 v28, s3
	ds_read_b128 v[8:11], v28
	ds_read_b128 v[12:15], v28 offset:16
	ds_read_b128 v[16:19], v28 offset:4096
	ds_read_b128 v[20:23], v28 offset:4112
	ds_read_b128 v[24:27], v28 offset:8192
	ds_read_b128 v[28:31], v28 offset:8208
	s_add_i32 s3, s3, 32
	s_waitcnt lgkmcnt(0)
	s_waitcnt vmcnt(55)
	v_fmac_f32_e32 v1, v104, v8
	v_fmac_f32_e32 v5, v104, v16
	v_fmac_f32_e32 v4, v104, v24
	s_waitcnt vmcnt(54)
	v_fmac_f32_e32 v1, v105, v9
	v_fmac_f32_e32 v5, v105, v17
	v_fmac_f32_e32 v4, v105, v25
	s_waitcnt vmcnt(53)
	v_fmac_f32_e32 v1, v106, v10
	v_fmac_f32_e32 v5, v106, v18
	v_fmac_f32_e32 v4, v106, v26
	s_waitcnt vmcnt(52)
	v_fmac_f32_e32 v1, v107, v11
	v_fmac_f32_e32 v5, v107, v19
	v_fmac_f32_e32 v4, v107, v27
	s_waitcnt vmcnt(51)
	v_fmac_f32_e32 v1, v108, v12
	v_fmac_f32_e32 v5, v108, v20
	v_fmac_f32_e32 v4, v108, v28
	s_waitcnt vmcnt(50)
	v_fmac_f32_e32 v1, v109, v13
	v_fmac_f32_e32 v5, v109, v21
	v_fmac_f32_e32 v4, v109, v29
	s_waitcnt vmcnt(49)
	v_fmac_f32_e32 v1, v110, v14
	v_fmac_f32_e32 v5, v110, v22
	v_fmac_f32_e32 v4, v110, v30
	s_waitcnt vmcnt(48)
	v_fmac_f32_e32 v1, v111, v15
	v_fmac_f32_e32 v5, v111, v23
	v_fmac_f32_e32 v4, v111, v31
	v_mov_b32_e32 v28, s3
	ds_read_b128 v[8:11], v28
	ds_read_b128 v[12:15], v28 offset:16
	ds_read_b128 v[16:19], v28 offset:4096
	ds_read_b128 v[20:23], v28 offset:4112
	ds_read_b128 v[24:27], v28 offset:8192
	ds_read_b128 v[28:31], v28 offset:8208
	s_add_i32 s3, s3, 32
	s_waitcnt lgkmcnt(0)
	s_waitcnt vmcnt(47)
	v_fmac_f32_e32 v1, v112, v8
	v_fmac_f32_e32 v5, v112, v16
	v_fmac_f32_e32 v4, v112, v24
	s_waitcnt vmcnt(46)
	v_fmac_f32_e32 v1, v113, v9
	v_fmac_f32_e32 v5, v113, v17
	v_fmac_f32_e32 v4, v113, v25
	s_waitcnt vmcnt(45)
	v_fmac_f32_e32 v1, v114, v10
	v_fmac_f32_e32 v5, v114, v18
	v_fmac_f32_e32 v4, v114, v26
	s_waitcnt vmcnt(44)
	v_fmac_f32_e32 v1, v115, v11
	v_fmac_f32_e32 v5, v115, v19
	v_fmac_f32_e32 v4, v115, v27
	s_waitcnt vmcnt(43)
	v_fmac_f32_e32 v1, v116, v12
	v_fmac_f32_e32 v5, v116, v20
	v_fmac_f32_e32 v4, v116, v28
	s_waitcnt vmcnt(42)
	v_fmac_f32_e32 v1, v117, v13
	v_fmac_f32_e32 v5, v117, v21
	v_fmac_f32_e32 v4, v117, v29
	s_waitcnt vmcnt(41)
	v_fmac_f32_e32 v1, v118, v14
	v_fmac_f32_e32 v5, v118, v22
	v_fmac_f32_e32 v4, v118, v30
	s_waitcnt vmcnt(40)
	v_fmac_f32_e32 v1, v119, v15
	v_fmac_f32_e32 v5, v119, v23
	v_fmac_f32_e32 v4, v119, v31
	v_mov_b32_e32 v28, s3
	ds_read_b128 v[8:11], v28
	ds_read_b128 v[12:15], v28 offset:16
	ds_read_b128 v[16:19], v28 offset:4096
	ds_read_b128 v[20:23], v28 offset:4112
	ds_read_b128 v[24:27], v28 offset:8192
	ds_read_b128 v[28:31], v28 offset:8208
	s_add_i32 s3, s3, 32
	s_waitcnt lgkmcnt(0)
	s_waitcnt vmcnt(39)
	v_fmac_f32_e32 v1, v120, v8
	v_fmac_f32_e32 v5, v120, v16
	v_fmac_f32_e32 v4, v120, v24
	s_waitcnt vmcnt(38)
	v_fmac_f32_e32 v1, v121, v9
	v_fmac_f32_e32 v5, v121, v17
	v_fmac_f32_e32 v4, v121, v25
	s_waitcnt vmcnt(37)
	v_fmac_f32_e32 v1, v122, v10
	v_fmac_f32_e32 v5, v122, v18
	v_fmac_f32_e32 v4, v122, v26
	s_waitcnt vmcnt(36)
	v_fmac_f32_e32 v1, v123, v11
	v_fmac_f32_e32 v5, v123, v19
	v_fmac_f32_e32 v4, v123, v27
	s_waitcnt vmcnt(35)
	v_fmac_f32_e32 v1, v124, v12
	v_fmac_f32_e32 v5, v124, v20
	v_fmac_f32_e32 v4, v124, v28
	s_waitcnt vmcnt(34)
	v_fmac_f32_e32 v1, v125, v13
	v_fmac_f32_e32 v5, v125, v21
	v_fmac_f32_e32 v4, v125, v29
	s_waitcnt vmcnt(33)
; __global__ void __launch_bounds__(NTHREADS) fwd_megakernel(Args a) {
;     ...
;         const bool act = lane < 36; const int j = bx * 36 + (act ? lane : 0), kb = wave * 128;
;         float s0 = 0.f, s1 = 0.f, s2 = 0.f;
;         if (act) {
; #pragma unroll 8
;         for (int kk = 0; kk < 128; ++kk) { const float w = __builtin_nontemporal_load(a.w_mod + (size_t)(kb + kk) * NMOD + j); s0 += sil[kb + kk] * w; s1 += sil[1024 + kb + kk] * w; s2 += sil[2048 + kb + kk] * w; }
;         }
	v_fmac_f32_e32 v1, v126, v14
	v_fmac_f32_e32 v5, v126, v22
	v_fmac_f32_e32 v4, v126, v30
	s_waitcnt vmcnt(32)
	v_fmac_f32_e32 v1, v127, v15
	v_fmac_f32_e32 v5, v127, v23
	v_fmac_f32_e32 v4, v127, v31
	v_mov_b32_e32 v28, s3
	ds_read_b128 v[8:11], v28
	ds_read_b128 v[12:15], v28 offset:16
	ds_read_b128 v[16:19], v28 offset:4096
	ds_read_b128 v[20:23], v28 offset:4112
	ds_read_b128 v[24:27], v28 offset:8192
	ds_read_b128 v[28:31], v28 offset:8208
	s_add_i32 s3, s3, 32
	s_waitcnt lgkmcnt(0)
	s_waitcnt vmcnt(31)
	v_fmac_f32_e32 v1, v128, v8
	v_fmac_f32_e32 v5, v128, v16
	v_fmac_f32_e32 v4, v128, v24
	s_waitcnt vmcnt(30)
	v_fmac_f32_e32 v1, v129, v9
	v_fmac_f32_e32 v5, v129, v17
	v_fmac_f32_e32 v4, v129, v25
	s_waitcnt vmcnt(29)
	v_fmac_f32_e32 v1, v130, v10
	v_fmac_f32_e32 v5, v130, v18
	v_fmac_f32_e32 v4, v130, v26
	s_waitcnt vmcnt(28)
	v_fmac_f32_e32 v1, v131, v11
	v_fmac_f32_e32 v5, v131, v19
	v_fmac_f32_e32 v4, v131, v27
	s_waitcnt vmcnt(27)
	v_fmac_f32_e32 v1, v132, v12
	v_fmac_f32_e32 v5, v132, v20
	v_fmac_f32_e32 v4, v132, v28
	s_waitcnt vmcnt(26)
	v_fmac_f32_e32 v1, v133, v13
	v_fmac_f32_e32 v5, v133, v21
	v_fmac_f32_e32 v4, v133, v29
	s_waitcnt vmcnt(25)
	v_fmac_f32_e32 v1, v134, v14
	v_fmac_f32_e32 v5, v134, v22
	v_fmac_f32_e32 v4, v134, v30
	s_waitcnt vmcnt(24)
	v_fmac_f32_e32 v1, v135, v15
	v_fmac_f32_e32 v5, v135, v23
	v_fmac_f32_e32 v4, v135, v31
	v_mov_b32_e32 v28, s3
	ds_read_b128 v[8:11], v28
	ds_read_b128 v[12:15], v28 offset:16
	ds_read_b128 v[16:19], v28 offset:4096
	ds_read_b128 v[20:23], v28 offset:4112
	ds_read_b128 v[24:27], v28 offset:8192
	ds_read_b128 v[28:31], v28 offset:8208
	s_add_i32 s3, s3, 32
	s_waitcnt lgkmcnt(0)
	s_waitcnt vmcnt(23)
	v_fmac_f32_e32 v1, v136, v8
	v_fmac_f32_e32 v5, v136, v16
	v_fmac_f32_e32 v4, v136, v24
	s_waitcnt vmcnt(22)
	v_fmac_f32_e32 v1, v137, v9
	v_fmac_f32_e32 v5, v137, v17
	v_fmac_f32_e32 v4, v137, v25
	s_waitcnt vmcnt(21)
	v_fmac_f32_e32 v1, v138, v10
	v_fmac_f32_e32 v5, v138, v18
	v_fmac_f32_e32 v4, v138, v26
	s_waitcnt vmcnt(20)
	v_fmac_f32_e32 v1, v139, v11
	v_fmac_f32_e32 v5, v139, v19
	v_fmac_f32_e32 v4, v139, v27
	s_waitcnt vmcnt(19)
	v_fmac_f32_e32 v1, v140, v12
	v_fmac_f32_e32 v5, v140, v20
	v_fmac_f32_e32 v4, v140, v28
	s_waitcnt vmcnt(18)
	v_fmac_f32_e32 v1, v141, v13
	v_fmac_f32_e32 v5, v141, v21
	v_fmac_f32_e32 v4, v141, v29
	s_waitcnt vmcnt(17)
	v_fmac_f32_e32 v1, v142, v14
	v_fmac_f32_e32 v5, v142, v22
	v_fmac_f32_e32 v4, v142, v30
	s_waitcnt vmcnt(16)
	v_fmac_f32_e32 v1, v143, v15
	v_fmac_f32_e32 v5, v143, v23
	v_fmac_f32_e32 v4, v143, v31
	v_mov_b32_e32 v28, s3
	ds_read_b128 v[8:11], v28
	ds_read_b128 v[12:15], v28 offset:16
	ds_read_b128 v[16:19], v28 offset:4096
	ds_read_b128 v[20:23], v28 offset:4112
	ds_read_b128 v[24:27], v28 offset:8192
	ds_read_b128 v[28:31], v28 offset:8208
	s_add_i32 s3, s3, 32
	s_waitcnt lgkmcnt(0)
	s_waitcnt vmcnt(15)
	v_fmac_f32_e32 v1, v144, v8
	v_fmac_f32_e32 v5, v144, v16
	v_fmac_f32_e32 v4, v144, v24
	s_waitcnt vmcnt(14)
	v_fmac_f32_e32 v1, v145, v9
	v_fmac_f32_e32 v5, v145, v17
	v_fmac_f32_e32 v4, v145, v25
	s_waitcnt vmcnt(13)
	v_fmac_f32_e32 v1, v146, v10
	v_fmac_f32_e32 v5, v146, v18
	v_fmac_f32_e32 v4, v146, v26
	s_waitcnt vmcnt(12)
	v_fmac_f32_e32 v1, v147, v11
	v_fmac_f32_e32 v5, v147, v19
	v_fmac_f32_e32 v4, v147, v27
	s_waitcnt vmcnt(11)
	v_fmac_f32_e32 v1, v148, v12
	v_fmac_f32_e32 v5, v148, v20
	v_fmac_f32_e32 v4, v148, v28
	s_waitcnt vmcnt(10)
	v_fmac_f32_e32 v1, v149, v13
	v_fmac_f32_e32 v5, v149, v21
	v_fmac_f32_e32 v4, v149, v29
	s_waitcnt vmcnt(9)
	v_fmac_f32_e32 v1, v150, v14
	v_fmac_f32_e32 v5, v150, v22
	v_fmac_f32_e32 v4, v150, v30
	s_waitcnt vmcnt(8)
	v_fmac_f32_e32 v1, v151, v15
	v_fmac_f32_e32 v5, v151, v23
	v_fmac_f32_e32 v4, v151, v31
	v_mov_b32_e32 v28, s3
	ds_read_b128 v[8:11], v28
	ds_read_b128 v[12:15], v28 offset:16
	ds_read_b128 v[16:19], v28 offset:4096
	ds_read_b128 v[20:23], v28 offset:4112
	ds_read_b128 v[24:27], v28 offset:8192
	ds_read_b128 v[28:31], v28 offset:8208
	s_waitcnt lgkmcnt(0)
	s_waitcnt vmcnt(7)
	v_fmac_f32_e32 v1, v152, v8
	v_fmac_f32_e32 v5, v152, v16
	v_fmac_f32_e32 v4, v152, v24
	s_waitcnt vmcnt(6)
	v_fmac_f32_e32 v1, v153, v9
	v_fmac_f32_e32 v5, v153, v17
	v_fmac_f32_e32 v4, v153, v25
	s_waitcnt vmcnt(5)
	v_fmac_f32_e32 v1, v154, v10
	v_fmac_f32_e32 v5, v154, v18
	v_fmac_f32_e32 v4, v154, v26
	s_waitcnt vmcnt(4)
	v_fmac_f32_e32 v1, v155, v11
	v_fmac_f32_e32 v5, v155, v19
	v_fmac_f32_e32 v4, v155, v27
	s_waitcnt vmcnt(3)
	v_fmac_f32_e32 v1, v156, v12
	v_fmac_f32_e32 v5, v156, v20
	v_fmac_f32_e32 v4, v156, v28
	s_waitcnt vmcnt(2)
	v_fmac_f32_e32 v1, v157, v13
	v_fmac_f32_e32 v5, v157, v21
	v_fmac_f32_e32 v4, v157, v29
	s_waitcnt vmcnt(1)
	v_fmac_f32_e32 v1, v158, v14
	v_fmac_f32_e32 v5, v158, v22
	v_fmac_f32_e32 v4, v158, v30
	s_waitcnt vmcnt(0)
	v_fmac_f32_e32 v1, v159, v15
	v_fmac_f32_e32 v5, v159, v23
	v_fmac_f32_e32 v4, v159, v31

; __device__ __forceinline__ void xcd_barrier(const XcdBarrier& b) {
;     asm volatile("s_waitcnt vmcnt(0)" ::: "memory");
;     __syncthreads();
;     if (threadIdx.x == 0) {
; __global__ void __launch_bounds__(NTHREADS) fwd_megakernel(Args a) {
;     ...
;     if (bx < 16) {
;         pg8::Gemm g{R1, WIN, MT, 3072, DM}; pg8::CtxKVOrder S{bx}; pg8::EpiQKV E{Qb, Kb, Vb, rope};
;         pg8::gemm_phase(ldsl, g, S, E);
;     } else {
;         const float* md = mods + ((bx & 7) >> 2) * NMOD;
;         const PVec g1 = pmul(load_pvec(md + 2 * DM, lane), load_pvec(a.f1_post, lane));
;         const PVec gs = pmul1p(load_pvec(a.mix_pre, lane), load_pvec(md + 4 * DM, lane)), sh = load_pvec(md + 3 * DM, lane);
.LBB0_371:
	s_waitcnt vmcnt(0)
	s_waitcnt vmcnt(0)
	s_barrier
	s_cmp_lg_u64 s[92:93], 0
	s_cbranch_scc1 .Lpvpre_p3
	s_cmp_lt_u32 s20, 16
	s_cbranch_scc1 .Lpvpre_p3
	v_readlane_b32 s98, v238, 40
	s_nop 3
	s_add_i32 s98, s98, -1
	v_readlane_b32 s0, v238, 28
	v_mov_b32_e32 v165, 0
	v_readlane_b32 s1, v238, 29
	s_mov_b64 s[6:7], 0x4000
	s_movk_i32 s5, 0x3000
	v_lshl_add_u64 v[0:1], s[0:1], 0, v[164:165]
	s_mov_b64 s[0:1], 0x2000
	v_lshl_add_u64 v[2:3], v[0:1], 0, s[0:1]
	s_movk_i32 s0, 0x4000
	v_add_co_u32_e64 v6, s[0:1], s0, v0
	s_cmp_lg_u32 s98, 0
	s_cbranch_scc1 .Lpv_p3_0
	global_load_dwordx4 v[176:179], v[2:3], off offset:1024

; __device__ __forceinline__ void xcd_barrier(const XcdBarrier& b) {
;     asm volatile("s_waitcnt vmcnt(0)" ::: "memory");
;     __syncthreads();
;     if (threadIdx.x == 0) {
;         unsigned* bar = b.bar;
;         __builtin_amdgcn_s_waitcnt(0);
;         unsigned nloc = b.st[0], nx = b.st[1];
;         if (nloc == 0u) { xcd_barrier_complete(bar, b.x, nloc, nx); b.st[0] = nloc; b.st[1] = nx; }
; __global__ void __launch_bounds__(NTHREADS) fwd_megakernel(Args a) {
;     ...
;         float d1 = 0.f, d2 = 0.f;
;         for (int i = 0; i < 64; ++i) { d1 += a.lq1[i] * a.lk1[i]; d2 += a.lq2[i] * a.lk2[i]; }
.LBB0_634:
	s_waitcnt vmcnt(0)
	s_waitcnt vmcnt(0)
	s_barrier
	s_cmp_lg_u64 s[92:93], 0
	s_cbranch_scc1 .Llam_pre
	v_readlane_b32 s98, v238, 40
	v_mbcnt_lo_u32_b32 v3, -1, 0
	v_mbcnt_hi_u32_b32 v3, -1, v3
	v_lshlrev_b32_e32 v3, 2, v3
	s_nop 1
	s_cmp_lg_u32 s98, 1
	s_cbranch_scc1 .Llam_w1
	global_load_dword v134, v3, s[80:81]
	s_waitcnt vmcnt(0)
	ds_write_b32 v3, v134
	s_waitcnt lgkmcnt(0)
.Llam_w1:
	s_cmp_lg_u32 s98, 2
	s_cbranch_scc1 .Llam_w2
	global_load_dword v134, v3, s[82:83]
	s_waitcnt vmcnt(0)
	ds_write_b32 v3, v134 offset:256
	s_waitcnt lgkmcnt(0)
.Llam_w2:
	s_cmp_lg_u32 s98, 3
	s_cbranch_scc1 .Llam_w3
	global_load_dword v134, v3, s[52:53]
	s_waitcnt vmcnt(0)
	ds_write_b32 v3, v134 offset:512
	s_waitcnt lgkmcnt(0)
.Llam_w3:
	s_cmp_lg_u32 s98, 4
	s_cbranch_scc1 .Llam_w4
	global_load_dword v134, v3, s[54:55]
	s_waitcnt vmcnt(0)
	ds_write_b32 v3, v134 offset:768
	s_waitcnt lgkmcnt(0)
.Llam_w4:
.Llam_pre:
	s_and_saveexec_b64 s[0:1], s[92:93]
	v_readlane_b32 s86, v238, 30
	v_readlane_b32 s87, v238, 31
	s_cbranch_execz .LBB0_686
	s_add_i32 s4, 0, 0x23fe0
	v_mov_b32_e32 v0, s4
	s_waitcnt vmcnt(0) expcnt(0) lgkmcnt(0)
	ds_read_b32 v2, v0
	s_add_i32 s4, 0, 0x23fe4
	v_mov_b32_e32 v0, s4
	ds_read_b32 v0, v0
	s_waitcnt lgkmcnt(1)
	v_cmp_ne_u32_e32 vcc, 0, v2
	s_cbranch_vccnz .LBB0_650
	s_add_u32 s4, s30, 0x1000
	s_addc_u32 s5, s31, 0
	s_add_u32 s6, s30, 0x1100
	s_addc_u32 s7, s31, 0
	s_add_u32 s8, s30, 0x1200
	s_addc_u32 s9, s31, 0
	s_mul_i32 s16, s91, s85
	s_add_u32 s10, s30, 0x1300
	s_mul_i32 s16, s16, s90
	s_addc_u32 s11, s31, 0
	s_mov_b32 s17, 1
	v_mov_b32_e32 v16, 0
	s_branch .LBB0_638

; __global__ void __launch_bounds__(NTHREADS) fwd_megakernel(Args a) {
;     ...
;         float d1 = 0.f, d2 = 0.f;
;         for (int i = 0; i < 64; ++i) { d1 += a.lq1[i] * a.lk1[i]; d2 += a.lq2[i] * a.lk2[i]; }
;         const float lam = expf(d1) - expf(d2) + LAM_INIT;
.LBB0_687:
	v_mov_b32_e32 v133, 0
	ds_read_b128 v[4:7], v133 offset:0
	ds_read_b128 v[8:11], v133 offset:16
	ds_read_b128 v[12:15], v133 offset:32
	ds_read_b128 v[16:19], v133 offset:48
	ds_read_b128 v[20:23], v133 offset:64
	ds_read_b128 v[24:27], v133 offset:80
	ds_read_b128 v[28:31], v133 offset:96
	ds_read_b128 v[32:35], v133 offset:112
	ds_read_b128 v[36:39], v133 offset:256
	ds_read_b128 v[40:43], v133 offset:272
	ds_read_b128 v[44:47], v133 offset:288
	ds_read_b128 v[48:51], v133 offset:304
	ds_read_b128 v[52:55], v133 offset:320
	ds_read_b128 v[56:59], v133 offset:336
	ds_read_b128 v[60:63], v133 offset:352
	ds_read_b128 v[64:67], v133 offset:368
	ds_read_b128 v[68:71], v133 offset:512
	ds_read_b128 v[72:75], v133 offset:528
	ds_read_b128 v[76:79], v133 offset:544
	ds_read_b128 v[80:83], v133 offset:560
	ds_read_b128 v[84:87], v133 offset:576
	ds_read_b128 v[88:91], v133 offset:592
	ds_read_b128 v[92:95], v133 offset:608
	ds_read_b128 v[96:99], v133 offset:624
	ds_read_b128 v[100:103], v133 offset:768
	ds_read_b128 v[104:107], v133 offset:784
	ds_read_b128 v[108:111], v133 offset:800
	ds_read_b128 v[112:115], v133 offset:816
	ds_read_b128 v[116:119], v133 offset:832
	ds_read_b128 v[120:123], v133 offset:848
	ds_read_b128 v[124:127], v133 offset:864
	ds_read_b128 v[128:131], v133 offset:880
	s_waitcnt lgkmcnt(0)
	v_fma_f32 v0, v4, v36, v0
	v_fma_f32 v1, v68, v100, v1
	v_fma_f32 v0, v5, v37, v0
	v_fma_f32 v1, v69, v101, v1
	v_fma_f32 v0, v6, v38, v0
	v_fma_f32 v1, v70, v102, v1
	v_fma_f32 v0, v7, v39, v0
	v_fma_f32 v1, v71, v103, v1
	v_fma_f32 v0, v8, v40, v0
	v_fma_f32 v1, v72, v104, v1
	v_fma_f32 v0, v9, v41, v0
	v_fma_f32 v1, v73, v105, v1
	v_fma_f32 v0, v10, v42, v0
	v_fma_f32 v1, v74, v106, v1
	v_fma_f32 v0, v11, v43, v0
	v_fma_f32 v1, v75, v107, v1
	v_fma_f32 v0, v12, v44, v0
	v_fma_f32 v1, v76, v108, v1
	v_fma_f32 v0, v13, v45, v0
	v_fma_f32 v1, v77, v109, v1
	v_fma_f32 v0, v14, v46, v0
	v_fma_f32 v1, v78, v110, v1
	v_fma_f32 v0, v15, v47, v0
	v_fma_f32 v1, v79, v111, v1
	v_fma_f32 v0, v16, v48, v0
	v_fma_f32 v1, v80, v112, v1
	v_fma_f32 v0, v17, v49, v0
	v_fma_f32 v1, v81, v113, v1
	v_fma_f32 v0, v18, v50, v0
	v_fma_f32 v1, v82, v114, v1
	v_fma_f32 v0, v19, v51, v0
	v_fma_f32 v1, v83, v115, v1
	v_fma_f32 v0, v20, v52, v0
	v_fma_f32 v1, v84, v116, v1
	v_fma_f32 v0, v21, v53, v0
	v_fma_f32 v1, v85, v117, v1
	v_fma_f32 v0, v22, v54, v0
	v_fma_f32 v1, v86, v118, v1
	v_fma_f32 v0, v23, v55, v0
	v_fma_f32 v1, v87, v119, v1
	v_fma_f32 v0, v24, v56, v0
	v_fma_f32 v1, v88, v120, v1
	v_fma_f32 v0, v25, v57, v0
	v_fma_f32 v1, v89, v121, v1
	v_fma_f32 v0, v26, v58, v0
	v_fma_f32 v1, v90, v122, v1
	v_fma_f32 v0, v27, v59, v0
	v_fma_f32 v1, v91, v123, v1
	v_fma_f32 v0, v28, v60, v0
	v_fma_f32 v1, v92, v124, v1
	v_fma_f32 v0, v29, v61, v0
	v_fma_f32 v1, v93, v125, v1
	v_fma_f32 v0, v30, v62, v0
	v_fma_f32 v1, v94, v126, v1
	v_fma_f32 v0, v31, v63, v0
	v_fma_f32 v1, v95, v127, v1
	v_fma_f32 v0, v32, v64, v0
	v_fma_f32 v1, v96, v128, v1
	v_fma_f32 v0, v33, v65, v0
	v_fma_f32 v1, v97, v129, v1
	v_fma_f32 v0, v34, v66, v0
	v_fma_f32 v1, v98, v130, v1
	v_fma_f32 v0, v35, v67, v0
	v_fma_f32 v1, v99, v131, v1
	ds_read_b128 v[4:7], v133 offset:128
	ds_read_b128 v[8:11], v133 offset:144
	ds_read_b128 v[12:15], v133 offset:160
	ds_read_b128 v[16:19], v133 offset:176
	ds_read_b128 v[20:23], v133 offset:192
	ds_read_b128 v[24:27], v133 offset:208
	ds_read_b128 v[28:31], v133 offset:224
	ds_read_b128 v[32:35], v133 offset:240
	ds_read_b128 v[36:39], v133 offset:384
	ds_read_b128 v[40:43], v133 offset:400
	ds_read_b128 v[44:47], v133 offset:416
	ds_read_b128 v[48:51], v133 offset:432
	ds_read_b128 v[52:55], v133 offset:448
	ds_read_b128 v[56:59], v133 offset:464
	ds_read_b128 v[60:63], v133 offset:480
	ds_read_b128 v[64:67], v133 offset:496
	ds_read_b128 v[68:71], v133 offset:640
	ds_read_b128 v[72:75], v133 offset:656
	ds_read_b128 v[76:79], v133 offset:672
	ds_read_b128 v[80:83], v133 offset:688
	ds_read_b128 v[84:87], v133 offset:704
	ds_read_b128 v[88:91], v133 offset:720
	ds_read_b128 v[92:95], v133 offset:736
	ds_read_b128 v[96:99], v133 offset:752
	ds_read_b128 v[100:103], v133 offset:896
	ds_read_b128 v[104:107], v133 offset:912
	ds_read_b128 v[108:111], v133 offset:928
	ds_read_b128 v[112:115], v133 offset:944
	ds_read_b128 v[116:119], v133 offset:960
	ds_read_b128 v[120:123], v133 offset:976
	ds_read_b128 v[124:127], v133 offset:992
	ds_read_b128 v[128:131], v133 offset:1008
	s_waitcnt lgkmcnt(0)
	v_fma_f32 v0, v4, v36, v0
	v_fma_f32 v1, v68, v100, v1
	v_fma_f32 v0, v5, v37, v0
	v_fma_f32 v1, v69, v101, v1
	v_fma_f32 v0, v6, v38, v0
	v_fma_f32 v1, v70, v102, v1
	v_fma_f32 v0, v7, v39, v0
	v_fma_f32 v1, v71, v103, v1
	v_fma_f32 v0, v8, v40, v0
	v_fma_f32 v1, v72, v104, v1
	v_fma_f32 v0, v9, v41, v0
	v_fma_f32 v1, v73, v105, v1
	v_fma_f32 v0, v10, v42, v0
	v_fma_f32 v1, v74, v106, v1
	v_fma_f32 v0, v11, v43, v0
	v_fma_f32 v1, v75, v107, v1
	v_fma_f32 v0, v12, v44, v0
	v_fma_f32 v1, v76, v108, v1
	v_fma_f32 v0, v13, v45, v0
	v_fma_f32 v1, v77, v109, v1
	v_fma_f32 v0, v14, v46, v0
	v_fma_f32 v1, v78, v110, v1
	v_fma_f32 v0, v15, v47, v0
	v_fma_f32 v1, v79, v111, v1
	v_fma_f32 v0, v16, v48, v0
	v_fma_f32 v1, v80, v112, v1
	v_fma_f32 v0, v17, v49, v0
	v_fma_f32 v1, v81, v113, v1
	v_fma_f32 v0, v18, v50, v0
	v_fma_f32 v1, v82, v114, v1
	v_fma_f32 v0, v19, v51, v0
	v_fma_f32 v1, v83, v115, v1
	v_fma_f32 v0, v20, v52, v0
	v_fma_f32 v1, v84, v116, v1
	v_fma_f32 v0, v21, v53, v0
	v_fma_f32 v1, v85, v117, v1
	v_fma_f32 v0, v22, v54, v0
	v_fma_f32 v1, v86, v118, v1
	v_fma_f32 v0, v23, v55, v0
	v_fma_f32 v1, v87, v119, v1
	v_fma_f32 v0, v24, v56, v0
	v_fma_f32 v1, v88, v120, v1
	v_fma_f32 v0, v25, v57, v0
	v_fma_f32 v1, v89, v121, v1
	v_fma_f32 v0, v26, v58, v0
	v_fma_f32 v1, v90, v122, v1
	v_fma_f32 v0, v27, v59, v0
	v_fma_f32 v1, v91, v123, v1
	v_fma_f32 v0, v28, v60, v0
	v_fma_f32 v1, v92, v124, v1
	v_fma_f32 v0, v29, v61, v0
	v_fma_f32 v1, v93, v125, v1
	v_fma_f32 v0, v30, v62, v0
	v_fma_f32 v1, v94, v126, v1
	v_fma_f32 v0, v31, v63, v0
	v_fma_f32 v1, v95, v127, v1
	v_fma_f32 v0, v32, v64, v0
	v_fma_f32 v1, v96, v128, v1
	v_fma_f32 v0, v33, v65, v0
	v_fma_f32 v1, v97, v129, v1
	v_fma_f32 v0, v34, v66, v0
	v_fma_f32 v1, v98, v130, v1
	v_fma_f32 v0, v35, v67, v0
	v_fma_f32 v1, v99, v131, v1
	s_add_u32 s21, s30, 0xde00000
	s_addc_u32 s82, s31, 0
	s_cmpk_gt_i32 s2, 0x1ff
	s_cbranch_scc1 .LBB0_745
; __global__ void __launch_bounds__(NTHREADS) fwd_megakernel(Args a) {
;     ...
;         const float lam = expf(d1) - expf(d2) + LAM_INIT;
;         for (int u = vcu; u < NB * 8 * (SEQ / 256); u += G) {
;             const int bh = u >> 5, qb = u & 31;
;             att::attn_unit(bh >> 3, bh & 7, qb, Qb, Kb, Vb, Ob, (bf16_t*)a.out, a.subln, lam, (char*)lds);
	v_mul_f32_e32 v2, 0x3fb8aa3b, v0
	s_mov_b32 s0, 0x3fb8aa3b
	v_rndne_f32_e32 v3, v2
	v_sub_f32_e32 v4, v2, v3
	v_fma_f32 v2, v0, s0, -v2
	v_fmac_f32_e32 v2, 0x32a5705f, v0
	v_add_f32_e32 v2, v4, v2
	v_exp_f32_e32 v2, v2
	v_cvt_i32_f32_e32 v3, v3
	s_mov_b32 s1, 0xc2ce8ed0
	v_cmp_ngt_f32_e32 vcc, s1, v0
	s_mov_b32 s4, 0x42b17218
	v_ldexp_f32 v2, v2, v3
	v_mul_f32_e32 v3, 0x3fb8aa3b, v1
	v_rndne_f32_e32 v4, v3
	v_sub_f32_e32 v5, v3, v4
	v_fma_f32 v3, v1, s0, -v3
	v_fmac_f32_e32 v3, 0x32a5705f, v1
	v_add_f32_e32 v3, v5, v3
	v_exp_f32_e32 v3, v3
	v_cvt_i32_f32_e32 v4, v4
	v_cndmask_b32_e32 v2, 0, v2, vcc
	v_mov_b32_e32 v5, 0x7f800000
	v_cmp_nlt_f32_e32 vcc, s4, v0
	s_add_u32 s16, s30, 0xbc40000
	s_mov_b32 s7, 0
	v_cndmask_b32_e32 v0, v5, v2, vcc
	v_ldexp_f32 v2, v3, v4
	v_cmp_ngt_f32_e32 vcc, s1, v1
	s_addc_u32 s17, s31, 0
	s_lshl_b32 s23, s2, 2
	v_cndmask_b32_e32 v2, 0, v2, vcc
	v_cmp_nlt_f32_e32 vcc, s4, v1
	s_lshl_b32 s46, s90, 2
	v_mov_b32_e32 v167, 0
	v_cndmask_b32_e32 v1, v5, v2, vcc
	v_sub_f32_e32 v0, v0, v1
	v_add_f32_e32 v163, 0x3e4ccccd, v0
	s_mov_b64 s[8:9], 0x20000
	s_mov_b32 s47, 0x4138aa3b
	s_mov_b64 s[10:11], 0x40000
	s_add_i32 s72, 0, 0x10000
	s_mov_b64 s[12:13], 0x20080
	v_mov_b32_e32 v165, 0x358637bd
	s_mov_b32 s73, 0xf800000
	v_mov_b32_e32 v175, 0x260
	s_mov_b32 s74, 0x3f4ccccd
	s_movk_i32 s75, 0x2000
	v_mbcnt_hi_u32_b32 v176, -1, v174
	s_branch .LBB0_691

; __device__ __forceinline__ void xcd_barrier(const XcdBarrier& b) {
;     asm volatile("s_waitcnt vmcnt(0)" ::: "memory");
;     __syncthreads();
;     if (threadIdx.x == 0) {
; __global__ void __launch_bounds__(NTHREADS) fwd_megakernel(Args a) {
;     ...
;     f32x4 cw[2][6];
; #pragma unroll
;     for (int j = 0; j < 2; ++j) { const int col = 8 * lane + 512 * j;
; #pragma unroll
;         for (int q = 0; q < 3; ++q) { cw[j][2 * q] = *(const f32x4*)(a.conv_w + q * DM + col); cw[j][2 * q + 1] = *(const f32x4*)(a.conv_w + q * DM + col + 4); } }
.LBB0_879:
	s_waitcnt vmcnt(0)
	s_waitcnt vmcnt(0)
	s_barrier
	s_cmp_lg_u64 s[92:93], 0
	s_cbranch_scc1 .Lpvpre_p6
	v_readlane_b32 s98, v238, 40
	s_nop 3
	s_add_i32 s98, s98, -1
	v_mov_b32_e32 v49, 0
	v_lshlrev_b32_e32 v48, 5, v161
	v_lshl_add_u64 v[24:25], s[58:59], 0, v[48:49]
	s_mov_b64 s[0:1], 0x2800
	v_lshl_add_u64 v[16:17], v[24:25], 0, s[0:1]
	v_add_co_u32_e32 v20, vcc, 0x2000, v24
	s_mov_b64 s[0:1], 0x1800
	s_nop 0
	v_addc_co_u32_e32 v21, vcc, 0, v25, vcc
	v_lshl_add_u64 v[4:5], v[24:25], 0, s[0:1]
	s_mov_b64 s[0:1], 0x2000
	v_add_co_u32_e32 v28, vcc, 0x1000, v24
	v_lshl_add_u64 v[32:33], v[24:25], 0, s[0:1]
	s_mov_b64 s[0:1], 0x1000
	v_addc_co_u32_e32 v29, vcc, 0, v25, vcc
	v_lshl_add_u64 v[36:37], v[24:25], 0, s[0:1]
	s_cmp_lg_u32 s98, 0
	s_cbranch_scc1 .Lpv_p6_0
	global_load_dwordx4 v[176:179], v[20:21], off offset:2048
.Lpv_p6_0:
	s_nop 0
	s_cmp_lg_u32 s98, 1
	s_cbranch_scc1 .Lpv_p6_1
	global_load_dwordx4 v[176:179], v[4:5], off offset:16
.Lpv_p6_1:
	s_nop 0
	s_cmp_lg_u32 s98, 2
	s_cbranch_scc1 .Lpv_p6_2
	global_load_dwordx4 v[176:179], v48, s[58:59] offset:2048
.Lpv_p6_2:
	s_cmp_lg_u32 s98, 3
	s_cbranch_scc1 .Lpv_p6_3
	global_load_dwordx4 v[176:179], v48, s[58:59] offset:2064
.Lpv_p6_3:
	s_nop 0
	s_cmp_lg_u32 s98, 4
	s_cbranch_scc1 .Lpv_p6_4
	global_load_dwordx4 v[176:179], v[16:17], off offset:16
.Lpv_p6_4:
	s_nop 0
	s_cmp_lg_u32 s98, 5
	s_cbranch_scc1 .Lpv_p6_5
	global_load_dwordx4 v[176:179], v[20:21], off
.Lpv_p6_5:
	s_nop 0
	s_cmp_lg_u32 s98, 6
	s_cbranch_scc1 .Lpv_p6_6
	global_load_dwordx4 v[176:179], v[28:29], off offset:2048
.Lpv_p6_6:
	s_nop 0
	s_cmp_lg_u32 s98, 0
	s_cbranch_scc1 .Lpv_p6_7
	global_load_dwordx4 v[180:183], v[28:29], off
.Lpv_p6_7:
	s_nop 0
	s_cmp_lg_u32 s98, 1
	s_cbranch_scc1 .Lpv_p6_8
	global_load_dwordx4 v[180:183], v[32:33], off offset:16
.Lpv_p6_8:
	s_nop 0
	s_cmp_lg_u32 s98, 2
	s_cbranch_scc1 .Lpv_p6_9
	global_load_dwordx4 v[180:183], v[36:37], off offset:16
.Lpv_p6_9:
	s_nop 0
	s_cmp_lg_u32 s98, 3
	s_cbranch_scc1 .Lpv_p6_10
	global_load_dwordx4 v[180:183], v48, s[58:59]
.Lpv_p6_10:
	s_cmp_lg_u32 s98, 4
	s_cbranch_scc1 .Lpv_p6_11
	global_load_dwordx4 v[180:183], v48, s[58:59] offset:16

; __device__ __forceinline__ unsigned xb_ld(unsigned* p)              { return __hip_atomic_load(p, __ATOMIC_RELAXED, __HIP_MEMORY_SCOPE_AGENT); }
; __device__ __forceinline__ void xcd_barrier_complete(unsigned* bar, unsigned x, unsigned& nloc, unsigned& nx) {
;     const unsigned G = gridDim.x * gridDim.y * gridDim.z;
;     unsigned sum, cnt, mine, sp = 0u;
;     for (;;) {
;         sum = 0u; cnt = 0u; mine = 0u;
; #pragma unroll
;         for (unsigned j = 0; j < 16; ++j) { const unsigned c = xb_ld(&bar[XB_XCNT(j)]); sum += c; cnt += (c > 0u) ? 1u : 0u; mine = (j == x) ? c : mine; }
; __device__ __forceinline__ void xcd_barrier(const XcdBarrier& b) {
;     ...
;     if (threadIdx.x == 0) {
;         unsigned* bar = b.bar;
;         __builtin_amdgcn_s_waitcnt(0);
;         unsigned nloc = b.st[0], nx = b.st[1];
;         if (nloc == 0u) { xcd_barrier_complete(bar, b.x, nloc, nx); b.st[0] = nloc; b.st[1] = nx; }
.Lpvpre_p6:
	s_and_saveexec_b64 s[0:1], s[92:93]
	s_cbranch_execz .LBB0_931
	s_add_i32 s2, 0, 0x23fe0
	v_mov_b32_e32 v0, s2
	s_waitcnt vmcnt(0) expcnt(0) lgkmcnt(0)
	ds_read_b32 v2, v0
	s_add_i32 s2, 0, 0x23fe4
	v_mov_b32_e32 v0, s2
	ds_read_b32 v0, v0
	s_waitcnt lgkmcnt(1)
	v_cmp_ne_u32_e32 vcc, 0, v2
	s_cbranch_vccnz .LBB0_895
	s_add_u32 s4, s30, 0x1000
	s_addc_u32 s5, s31, 0
	s_add_u32 s6, s30, 0x1100
	s_addc_u32 s7, s31, 0
	s_add_u32 s10, s30, 0x1200
	s_addc_u32 s11, s31, 0
	s_mul_i32 s2, s91, s85
	s_add_u32 s12, s30, 0x1300
	s_mul_i32 s2, s2, s90
	s_addc_u32 s13, s31, 0
	s_mov_b32 s16, 1
	v_mov_b32_e32 v16, 0
	s_branch .LBB0_883

; __global__ void __launch_bounds__(NTHREADS) fwd_megakernel(Args a) {
;     ...
;     f32x4 cw[2][6];
; #pragma unroll
;     for (int j = 0; j < 2; ++j) { const int col = 8 * lane + 512 * j;
; #pragma unroll
;         for (int q = 0; q < 3; ++q) { cw[j][2 * q] = *(const f32x4*)(a.conv_w + q * DM + col); cw[j][2 * q + 1] = *(const f32x4*)(a.conv_w + q * DM + col + 4); } }
;     for (int row = xrow0; row < xrow1; row += 256) {
;         const int t = row & (SEQ - 1);
; #pragma unroll
;         for (int j = 0; j < 2; ++j) { const int col = 8 * lane + 512 * j;
;             const u32x4 zc = *(const u32x4*)(Zb + (size_t)row * DM + col);
.LBB0_931:
	s_or_b64 exec, exec, s[0:1]
	s_and_b64 vcc, exec, s[86:87]
	s_waitcnt lgkmcnt(0)
	s_barrier
	s_cbranch_vccz .LBB0_943
	v_mov_b32_e32 v49, 0
	v_lshlrev_b32_e32 v48, 5, v161
	v_lshl_add_u64 v[24:25], s[58:59], 0, v[48:49]
	s_mov_b64 s[0:1], 0x2800
	v_lshl_add_u64 v[16:17], v[24:25], 0, s[0:1]
	v_add_co_u32_e32 v20, vcc, 0x2000, v24
	s_mov_b64 s[0:1], 0x1800
	s_nop 0
	v_addc_co_u32_e32 v21, vcc, 0, v25, vcc
	v_lshl_add_u64 v[4:5], v[24:25], 0, s[0:1]
	s_mov_b64 s[0:1], 0x2000
	v_add_co_u32_e32 v28, vcc, 0x1000, v24
	v_lshl_add_u64 v[32:33], v[24:25], 0, s[0:1]
	s_mov_b64 s[0:1], 0x1000
	v_addc_co_u32_e32 v29, vcc, 0, v25, vcc
	v_lshl_add_u64 v[36:37], v[24:25], 0, s[0:1]
	s_nop 0
	s_nop 0
	s_nop 0
	s_nop 0
	s_nop 0
	s_nop 0
	s_nop 0
	s_nop 0
	s_nop 0
	ds_read_b128 v[0:3], v164
	ds_read_b128 v[4:7], v164 offset:1024
	ds_read_b128 v[8:11], v164 offset:2048
	ds_read_b128 v[12:15], v164 offset:3072
	ds_read_b128 v[16:19], v164 offset:4096
	ds_read_b128 v[20:23], v164 offset:5120
	ds_read_b128 v[24:27], v164 offset:6144
	ds_read_b128 v[28:31], v164 offset:7168
	ds_read_b128 v[32:35], v164 offset:8192
	ds_read_b128 v[36:39], v164 offset:9216
	ds_read_b128 v[40:43], v164 offset:10240
	ds_read_b128 v[44:47], v164 offset:11264
	s_waitcnt lgkmcnt(0)
	s_ashr_i32 s23, s22, 31
	s_lshl_b64 s[0:1], s[22:23], 11
	s_add_u32 s0, s30, s0
	v_mov_b32_e32 v163, v49
	s_addc_u32 s1, s31, s1
	v_lshl_add_u64 v[48:49], s[0:1], 0, v[162:163]
	s_mov_b64 s[0:1], 0x7b00000
	v_lshlrev_b32_e32 v66, 3, v161
	v_lshl_add_u64 v[68:69], v[48:49], 0, s[0:1]
	s_mov_b64 s[0:1], 0x80000
	s_mov_b32 s2, s22
	s_branch .LBB0_934

; __device__ __forceinline__ void xcd_barrier(const XcdBarrier& b) {
;     asm volatile("s_waitcnt vmcnt(0)" ::: "memory");
;     __syncthreads();
;     if (threadIdx.x == 0) {
; __global__ void __launch_bounds__(NTHREADS) fwd_megakernel(Args a) {
;     ...
;     { const float* md = mods + ((bx & 7) >> 2) * NMOD;
;       const PVec g1 = pmul(load_pvec(md + 2 * DM, lane), load_pvec(a.f1_post, lane)), g2 = pmul(load_pvec(md + 5 * DM, lane), load_pvec(a.mix_post, lane));
;       const PVec gs = pmul1p(load_pvec(a.f2_pre, lane), load_pvec(md + 7 * DM, lane)), sh = load_pvec(md + 6 * DM, lane);
.LBB0_1120:
	s_waitcnt vmcnt(0)
	s_waitcnt vmcnt(0)
	s_barrier
	s_cmp_lg_u64 s[92:93], 0
	s_cbranch_scc1 .Lpvpre_p9
	v_readlane_b32 s98, v238, 40
	s_nop 3
	s_add_i32 s98, s98, -1
	v_readlane_b32 s6, v238, 28
	v_mov_b32_e32 v165, 0
	v_readlane_b32 s7, v238, 29
	s_movk_i32 s2, 0x6000
	s_ashr_i32 s23, s22, 31
	v_lshl_add_u64 v[0:1], s[6:7], 0, v[164:165]
	s_mov_b64 s[6:7], 0x2000
	v_lshl_add_u64 v[2:3], v[0:1], 0, s[6:7]
	s_mov_b64 s[6:7], 0x5000
	v_lshl_add_u64 v[6:7], v[0:1], 0, s[6:7]
	v_add_co_u32_e64 v32, s[6:7], s2, v0
	s_movk_i32 s2, 0x7000
	s_nop 0
	v_addc_co_u32_e64 v33, s[6:7], 0, v1, s[6:7]
	s_mov_b64 s[6:7], 0x7000
	v_add_co_u32_e32 v4, vcc, 0x2000, v0
	s_cmp_lg_u32 s98, 0
	s_cbranch_scc1 .Lpv_p9_0
	global_load_dwordx4 v[176:179], v[2:3], off offset:1024

; __device__ __forceinline__ void xcd_barrier(const XcdBarrier& b) {
;     asm volatile("s_waitcnt vmcnt(0)" ::: "memory");
;     __syncthreads();
;     if (threadIdx.x == 0) {
; __global__ void __launch_bounds__(NTHREADS) fwd_megakernel(Args a) {
;     ...
;     { const float* md = mods + ((bx & 7) >> 2) * NMOD;
;       const PVec g3 = pmul(load_pvec(md + 8 * DM, lane), load_pvec(a.f2_post, lane));
.LBB0_1323:
	s_waitcnt vmcnt(0)
	s_waitcnt vmcnt(0)
	s_barrier
	s_cmp_lg_u64 s[92:93], 0
	s_cbranch_scc1 .Lpvpre_p12
	v_readlane_b32 s98, v238, 40
	s_nop 3
	s_add_i32 s98, s98, -1
	v_readlane_b32 s0, v238, 28
	v_mov_b32_e32 v165, 0
	v_readlane_b32 s1, v238, 29
	s_ashr_i32 s23, s22, 31
	s_lshl_b64 s[8:9], s[22:23], 11
	v_lshl_add_u64 v[0:1], s[0:1], 0, v[164:165]
	s_mov_b64 s[0:1], 0x8000
	v_lshl_add_u64 v[2:3], v[0:1], 0, s[0:1]
	v_add_co_u32_e32 v0, vcc, 0x8000, v0
	v_readlane_b32 s0, v238, 0
	v_readlane_b32 s1, v238, 1
	v_addc_co_u32_e32 v1, vcc, 0, v1, vcc
	s_cmp_lg_u32 s98, 0
	s_cbranch_scc1 .Lpv_p12_0
	global_load_dwordx4 v[176:179], v[2:3], off offset:1024

; __global__ void __launch_bounds__(NTHREADS) fwd_megakernel(Args a) {
;     ...
;     { const float* md = mods + ((bx & 7) >> 2) * NMOD;
;       const PVec g3 = pmul(load_pvec(md + 8 * DM, lane), load_pvec(a.f2_post, lane));
.Lpv_p12_1:
	s_nop 1
	s_cmp_lg_u32 s98, 2
	s_cbranch_scc1 .Lpv_p12_2
	global_load_dwordx4 v[176:179], v164, s[0:1]
.Lpv_p12_2:
	s_cmp_lg_u32 s98, 3
	s_cbranch_scc1 .Lpv_p12_3
	global_load_dwordx4 v[176:179], v164, s[0:1] offset:1024
.Lpv_p12_3:
	s_cmp_lg_u32 s98, 4
	s_cbranch_scc1 .Lpv_p12_4
	global_load_dwordx4 v[176:179], v164, s[0:1] offset:2048
.Lpv_p12_4:
	s_cmp_lg_u32 s98, 5
	s_cbranch_scc1 .Lpv_p12_5
	global_load_dwordx4 v[176:179], v[0:1], off
.Lpv_p12_5:
	s_cmp_lg_u32 s98, 6
	s_cbranch_scc1 .Lpv_p12_6
	global_load_dwordx4 v[176:179], v164, s[0:1] offset:3072
.Lpv_p12_6:
	s_cmp_lg_u32 s98, 0
	s_cbranch_scc1 .Lpv_p12_7
	global_load_dwordx4 v[180:183], v[2:3], off offset:3072

; __device__ __forceinline__ unsigned xb_ld(unsigned* p)              { return __hip_atomic_load(p, __ATOMIC_RELAXED, __HIP_MEMORY_SCOPE_AGENT); }
; __device__ __forceinline__ void xcd_barrier_complete(unsigned* bar, unsigned x, unsigned& nloc, unsigned& nx) {
;     const unsigned G = gridDim.x * gridDim.y * gridDim.z;
;     unsigned sum, cnt, mine, sp = 0u;
;     for (;;) {
;         sum = 0u; cnt = 0u; mine = 0u;
; #pragma unroll
;         for (unsigned j = 0; j < 16; ++j) { const unsigned c = xb_ld(&bar[XB_XCNT(j)]); sum += c; cnt += (c > 0u) ? 1u : 0u; mine = (j == x) ? c : mine; }
; __device__ __forceinline__ void xcd_barrier(const XcdBarrier& b) {
;     ...
;     if (threadIdx.x == 0) {
;         unsigned* bar = b.bar;
;         __builtin_amdgcn_s_waitcnt(0);
;         unsigned nloc = b.st[0], nx = b.st[1];
;         if (nloc == 0u) { xcd_barrier_complete(bar, b.x, nloc, nx); b.st[0] = nloc; b.st[1] = nx; }
.Lpvpre_p12:
	s_and_saveexec_b64 s[0:1], s[92:93]
	s_cbranch_execz .LBB0_1375
	s_add_i32 s2, 0, 0x23fe0
	v_mov_b32_e32 v0, s2
	s_waitcnt vmcnt(0) expcnt(0) lgkmcnt(0)
	ds_read_b32 v2, v0
	s_add_i32 s2, 0, 0x23fe4
	v_mov_b32_e32 v0, s2
	ds_read_b32 v0, v0
	s_waitcnt lgkmcnt(1)
	v_cmp_ne_u32_e32 vcc, 0, v2
	s_cbranch_vccnz .LBB0_1339
	s_add_u32 s2, s30, 0x1000
	s_addc_u32 s3, s31, 0
	s_add_u32 s6, s30, 0x1100
	s_addc_u32 s7, s31, 0
	s_add_u32 s8, s30, 0x1200
	s_addc_u32 s9, s31, 0
	s_mul_i32 s18, s91, s85
	s_add_u32 s10, s30, 0x1300
	s_mul_i32 s18, s18, s90
	s_addc_u32 s11, s31, 0
	s_mov_b32 s19, 1
	v_mov_b32_e32 v16, 0
	s_branch .LBB0_1327

; __global__ void __launch_bounds__(NTHREADS) fwd_megakernel(Args a) {
;     ...
;     { const float* md = mods + ((bx & 7) >> 2) * NMOD;
;       const PVec g3 = pmul(load_pvec(md + 8 * DM, lane), load_pvec(a.f2_post, lane));
;       for (int row = xrow0; row < xrow1; row += 256) {
;         f32x4 h[4], y[4]; load_row_f32(a.out + (size_t)row * DM, lane, h); load_row_bf16(Y3 + (size_t)row * DM, lane, y);
;         add_branch_r(h, y, 0.5f, g3);
;         store_row_f32(a.out + (size_t)row * DM, lane, h);
;       } }
.LBB0_1375:
	s_or_b64 exec, exec, s[0:1]
	s_and_b64 vcc, exec, s[4:5]
	s_waitcnt lgkmcnt(0)
	s_barrier
	s_cbranch_vccnz .LBB0_1378
	v_readlane_b32 s0, v238, 28
	v_mov_b32_e32 v165, 0
	v_readlane_b32 s1, v238, 29
	s_ashr_i32 s23, s22, 31
	s_lshl_b64 s[8:9], s[22:23], 11
	v_lshl_add_u64 v[0:1], s[0:1], 0, v[164:165]
	s_mov_b64 s[0:1], 0x8000
	v_lshl_add_u64 v[2:3], v[0:1], 0, s[0:1]
	v_add_co_u32_e32 v0, vcc, 0x8000, v0
	v_readlane_b32 s0, v238, 0
	v_readlane_b32 s1, v238, 1
	v_addc_co_u32_e32 v1, vcc, 0, v1, vcc
	s_nop 1
	ds_read_b128 v[6:9], v164
	ds_read_b128 v[10:13], v164 offset:1024
	ds_read_b128 v[14:17], v164 offset:2048
	ds_read_b128 v[28:31], v164 offset:3072
	ds_read_b128 v[32:35], v164 offset:4096
	ds_read_b128 v[36:39], v164 offset:5120
	ds_read_b128 v[40:43], v164 offset:6144
	ds_read_b128 v[44:47], v164 offset:7168
	s_waitcnt lgkmcnt(0)
	v_mbcnt_hi_u32_b32 v0, -1, v174
	v_and_b32_e32 v1, 64, v0
	v_xor_b32_e32 v2, 1, v0
	v_add_u32_e32 v1, 64, v1
	v_xor_b32_e32 v3, 2, v0
	v_cmp_lt_i32_e32 vcc, v2, v1
	v_xor_b32_e32 v4, 4, v0
	v_xor_b32_e32 v5, 8, v0
	v_cndmask_b32_e32 v2, v0, v2, vcc
	v_cmp_lt_i32_e32 vcc, v3, v1
	v_xor_b32_e32 v18, 16, v0
	v_xor_b32_e32 v19, 32, v0
	v_cndmask_b32_e32 v3, v0, v3, vcc
	v_cmp_lt_i32_e32 vcc, v4, v1
	s_add_u32 s8, s30, s8
	v_lshlrev_b32_e32 v164, 3, v161
	v_cndmask_b32_e32 v4, v0, v4, vcc
	v_cmp_lt_i32_e32 vcc, v5, v1
	s_addc_u32 s9, s31, s9
	s_lshl_b64 s[10:11], s[22:23], 12
	v_cndmask_b32_e32 v5, v0, v5, vcc
	v_cmp_lt_i32_e32 vcc, v18, v1
	v_readlane_b32 s4, v238, 4
	v_readlane_b32 s5, v238, 5
	v_cndmask_b32_e32 v18, v0, v18, vcc
	v_cmp_lt_i32_e32 vcc, v19, v1
	v_mov_b32_e32 v163, v165
	v_readlane_b32 s2, v238, 2
	v_cndmask_b32_e32 v0, v0, v19, vcc
	v_lshlrev_b32_e32 v27, 2, v0
	v_lshl_add_u64 v[0:1], s[8:9], 0, v[164:165]
	s_add_u32 s8, s28, s10
	s_addc_u32 s9, s29, s11
	v_readlane_b32 s3, v238, 3
	v_readlane_b32 s6, v238, 6
	s_mov_b64 s[0:1], 0xdb00600
	s_mov_b64 s[4:5], 0x800
	v_lshlrev_b32_e32 v22, 2, v2
	v_lshlrev_b32_e32 v23, 2, v3
	v_lshl_add_u64 v[2:3], s[8:9], 0, v[162:163]
	v_mov_b32_e32 v20, 0x358637bd
	s_mov_b32 s6, 0xf800000
	v_mov_b32_e32 v21, 0x260
	s_mov_b64 s[2:3], 0x80000
	v_lshlrev_b32_e32 v24, 2, v4
	v_lshlrev_b32_e32 v25, 2, v5
	v_lshlrev_b32_e32 v26, 2, v18
	v_lshl_add_u64 v[0:1], v[0:1], 0, s[0:1]
	v_lshl_add_u64 v[2:3], v[2:3], 0, s[4:5]
	s_mov_b64 s[4:5], 0x100000
	v_readlane_b32 s7, v238, 7
	s_waitcnt vmcnt(2)
	v_pk_mul_f32 v[14:15], v[36:37], v[14:15]
	v_pk_mul_f32 v[4:5], v[8:9], v[30:31]
	v_pk_mul_f32 v[6:7], v[6:7], v[28:29]
	v_pk_mul_f32 v[8:9], v[12:13], v[34:35]
	v_pk_mul_f32 v[10:11], v[10:11], v[32:33]
	v_pk_mul_f32 v[12:13], v[38:39], v[16:17]
	s_waitcnt vmcnt(0)
	v_pk_mul_f32 v[16:17], v[46:47], v[42:43]
	v_pk_mul_f32 v[18:19], v[44:45], v[40:41]
